# E2 + batch-1 indexer q/k rotary also moved from the rope phase into batch 0's selection phase
# baseline (speedup 1.0000x reference)
; __device__ __forceinline__ unsigned cvt_pk_bf16(float lo, float hi) { unsigned r; asm volatile("v_cvt_pk_bf16_f32 %0, %1, %2" : "=v"(r) : "v"(lo), "v"(hi)); return r; }
; __device__ __forceinline__ float shx(float v, int m, int lane) { return __int_as_float(__builtin_amdgcn_ds_bpermute((lane ^ m) << 2, __float_as_int(v))); }
; #define DPPF(v, ctrl) __int_as_float(__builtin_amdgcn_update_dpp(0, __float_as_int(v), (ctrl), 0xf, 0xf, false))
; template <bool NORM, int ROT> __device__ __forceinline__ void rope_chunk(bf16_t* p, const u32x4 w, const f32x4 (&tb)[4], const float* g, float sc, int lane) {
;     ...
;     constexpr int HALFL = ROT / 16;
;     const bool rot = (ROT == 128) || (j < 8); const bool first = (j & HALFL) == 0;
;     float o[8];
; #pragma unroll
;     for (int q = 0; q < 8; ++q) {
;         const float other = (ROT == 128) ? DPPF(x[q], 0x128)   : shx(x[q], HALFL, lane);
;         const float cs = tb[q >> 1][(q & 1) * 2], sn = tb[q >> 1][(q & 1) * 2 + 1];
;         const float r = first ? (x[q] * cs - other * sn) : (x[q] * cs + other * sn);
;         o[q] = (rot ? r : x[q]) * sc;
;     }
;     u32x4 ow; ow.x = cvt_pk_bf16(o[0], o[1]); ow.y = cvt_pk_bf16(o[2], o[3]); ow.z = cvt_pk_bf16(o[4], o[5]); ow.w = cvt_pk_bf16(o[6], o[7]);
;     *(u32x4*)(p + lane * 8) = ow;
; template <bool NORM, int ROT, bool PERTOK> __device__ __forceinline__ void rope_pass(bf16_t* base, int nchunks, const float* g, const float* tab, float sc, int gw, int NGW, int lane) {
;     ...
;     for (int it0 = gw * NB; it0 < nchunks; it0 += NGW * NB) {
;         u32x4 w[NB]; f32x4 tb[NB][4];
; #pragma unroll
;         for (int k = 0; k < NB; ++k) { const int it = it0 + k;
;             w[k] = *(const u32x4*)(base + (size_t)it * 512 + lane * 8);
;             const int pos = PERTOK ? ((it >> 2) & 8191) : (((it * 4) & 8191) + (lane >> 4));
;             const float* tp = tab + (size_t)pos * ROT + (j & (HALFL - 1)) * 16;
; #pragma unroll
;             for (int q = 0; q < 4; ++q) tb[k][q] = *(const f32x4*)(tp + q * 4); }
; #pragma unroll
;         for (int k = 0; k < NB; ++k) rope_chunk<NORM, ROT>(base + (size_t)(it0 + k) * 512, w[k], tb[k], g, sc, lane);
.LBB0_1077:
	v_add_co_u32_e32 v120, vcc, 0xffffe400, v106
	s_and_b32 s15, s1, 0x7ff80
	s_nop 0
	v_addc_co_u32_e32 v121, vcc, -1, v107, vcc
	flat_load_dwordx4 v[126:129], v[120:121]
	flat_load_dwordx4 v[4:7], v[106:107]
	s_lshl_b32 s18, s15, 2
	v_lshl_add_u64 v[0:1], v[104:105], 0, s[18:19]
	flat_load_dwordx4 v[88:91], v[0:1]
	flat_load_dwordx4 v[92:95], v[0:1] offset:16
	flat_load_dwordx4 v[84:87], v[0:1] offset:32
	flat_load_dwordx4 v[76:79], v[0:1] offset:48
	v_add_co_u32_e32 v118, vcc, 0xffffe800, v106
	s_add_i32 s21, s1, 64
	s_nop 0
	v_addc_co_u32_e32 v119, vcc, -1, v107, vcc
	v_add_co_u32_e32 v116, vcc, 0xffffec00, v106
	s_add_i32 s24, s1, 0x50
	s_nop 0
	v_addc_co_u32_e32 v117, vcc, -1, v107, vcc
	flat_load_dwordx4 v[130:133], v[118:119]
	flat_load_dwordx4 v[100:103], v[116:117]
	v_add_co_u32_e32 v114, vcc, 0xfffff000, v106
	s_add_i32 s18, s1, 0x70
	s_and_b32 s21, s21, 0x7ffc0
	v_addc_co_u32_e32 v115, vcc, -1, v107, vcc
	s_add_i32 s15, s1, 0x60
	s_and_b32 s24, s24, 0x7ffc0
	s_and_b32 s25, s18, 0x7ffc0
	s_lshl_b32 s18, s21, 2
	v_add_co_u32_e32 v112, vcc, 0xfffff400, v106
	s_and_b32 s15, s15, 0x7ffc0
	v_lshl_add_u64 v[0:1], v[104:105], 0, s[18:19]
	s_lshl_b32 s18, s24, 2
	v_addc_co_u32_e32 v113, vcc, -1, v107, vcc
	flat_load_dwordx4 v[72:75], v[0:1]
	flat_load_dwordx4 v[68:71], v[0:1] offset:16
	flat_load_dwordx4 v[64:67], v[0:1] offset:32
	flat_load_dwordx4 v[56:59], v[0:1] offset:48
	v_lshl_add_u64 v[0:1], v[104:105], 0, s[18:19]
	s_lshl_b32 s18, s15, 2
	v_add_co_u32_e32 v110, vcc, 0xfffff800, v106
	flat_load_dwordx4 v[52:55], v[0:1]
	flat_load_dwordx4 v[48:51], v[0:1] offset:16
	flat_load_dwordx4 v[44:47], v[0:1] offset:32
	flat_load_dwordx4 v[36:39], v[0:1] offset:48
	v_lshl_add_u64 v[0:1], v[104:105], 0, s[18:19]
	s_lshl_b32 s18, s25, 2
	v_addc_co_u32_e32 v111, vcc, -1, v107, vcc
	flat_load_dwordx4 v[96:99], v[114:115]
	flat_load_dwordx4 v[80:83], v[112:113]
	v_add_co_u32_e32 v108, vcc, 0xfffffc00, v106
	flat_load_dwordx4 v[32:35], v[0:1]
	flat_load_dwordx4 v[28:31], v[0:1] offset:16
	flat_load_dwordx4 v[24:27], v[0:1] offset:32
	flat_load_dwordx4 v[20:23], v[0:1] offset:48
	v_lshl_add_u64 v[0:1], v[104:105], 0, s[18:19]
	flat_load_dwordx4 v[60:63], v[110:111]
	v_addc_co_u32_e32 v109, vcc, -1, v107, vcc
	flat_load_dwordx4 v[16:19], v[0:1]
	flat_load_dwordx4 v[12:15], v[0:1] offset:16
	flat_load_dwordx4 v[8:11], v[0:1] offset:32
	s_nop 0
	flat_load_dwordx4 v[0:3], v[0:1] offset:48
	s_nop 0
	flat_load_dwordx4 v[40:43], v[108:109]
	s_add_i32 s14, s14, s20
	s_add_i32 s1, s1, s3
	s_cmp_lt_i32 s14, 0x8000
	s_waitcnt vmcnt(0) lgkmcnt(0)
	v_lshlrev_b32_e32 v125, 16, v126
	ds_bpermute_b32 v135, v124, v125
	v_and_b32_e32 v126, 0xffff0000, v126
	ds_bpermute_b32 v138, v124, v126
	v_lshlrev_b32_e32 v134, 16, v127
	v_and_b32_e32 v127, 0xffff0000, v127
	s_waitcnt lgkmcnt(1)
	v_mul_f32_e32 v135, v89, v135
	v_cndmask_b32_e64 v135, v135, -v135, s[6:7]
	v_fmac_f32_e32 v135, v88, v125
	v_cndmask_b32_e64 v125, v125, v135, s[4:5]
	s_waitcnt lgkmcnt(0)
	v_mul_f32_e32 v135, v91, v138
	ds_bpermute_b32 v138, v124, v134
	v_cndmask_b32_e64 v135, v135, -v135, s[6:7]
	v_fmac_f32_e32 v135, v90, v126
	v_cndmask_b32_e64 v126, v126, v135, s[4:5]
	v_lshlrev_b32_e32 v136, 16, v128
	s_waitcnt lgkmcnt(0)
	v_mul_f32_e32 v135, v93, v138
	ds_bpermute_b32 v138, v124, v127
	v_cndmask_b32_e64 v135, v135, -v135, s[6:7]
	v_fmac_f32_e32 v135, v92, v134
	v_cndmask_b32_e64 v134, v134, v135, s[4:5]
	v_and_b32_e32 v128, 0xffff0000, v128
	s_waitcnt lgkmcnt(0)
	v_mul_f32_e32 v135, v95, v138
	ds_bpermute_b32 v138, v124, v136
	v_cndmask_b32_e64 v135, v135, -v135, s[6:7]
	v_fmac_f32_e32 v135, v94, v127
	v_cndmask_b32_e64 v127, v127, v135, s[4:5]
	v_lshlrev_b32_e32 v137, 16, v129
	s_waitcnt lgkmcnt(0)
	v_mul_f32_e32 v135, v85, v138
	ds_bpermute_b32 v138, v124, v128
	v_cndmask_b32_e64 v135, v135, -v135, s[6:7]
	v_fmac_f32_e32 v135, v84, v136
	v_cndmask_b32_e64 v135, v136, v135, s[4:5]
	v_and_b32_e32 v129, 0xffff0000, v129
	s_waitcnt lgkmcnt(0)
	v_mul_f32_e32 v136, v87, v138
	ds_bpermute_b32 v138, v124, v137
	v_cndmask_b32_e64 v136, v136, -v136, s[6:7]
	v_fmac_f32_e32 v136, v86, v128
	v_cndmask_b32_e64 v128, v128, v136, s[4:5]
	v_mul_f32_e32 v126, 0x3db504f3, v126
	s_waitcnt lgkmcnt(0)
	v_mul_f32_e32 v136, v77, v138
	ds_bpermute_b32 v138, v124, v129
	v_cndmask_b32_e64 v136, v136, -v136, s[6:7]
	v_fmac_f32_e32 v136, v76, v137
	v_cndmask_b32_e64 v136, v137, v136, s[4:5]
	v_mul_f32_e32 v127, 0x3db504f3, v127
	s_waitcnt lgkmcnt(0)
	v_mul_f32_e32 v137, v79, v138
	v_cndmask_b32_e64 v137, v137, -v137, s[6:7]
	v_fmac_f32_e32 v137, v78, v129
	v_cndmask_b32_e64 v129, v129, v137, s[4:5]
	v_mul_f32_e32 v128, 0x3db504f3, v128
	v_mul_f32_e32 v129, 0x3db504f3, v129
	v_mul_f32_e32 v125, 0x3db504f3, v125
	v_mul_f32_e32 v134, 0x3db504f3, v134
	v_mul_f32_e32 v135, 0x3db504f3, v135
	v_mul_f32_e32 v136, 0x3db504f3, v136
	v_cvt_pk_bf16_f32 v126, v125, v126
	v_cvt_pk_bf16_f32 v127, v134, v127
	v_cvt_pk_bf16_f32 v128, v135, v128
	v_cvt_pk_bf16_f32 v129, v136, v129
	flat_store_dwordx4 v[120:121], v[126:129]
	v_lshlrev_b32_e32 v120, 16, v130
	ds_bpermute_b32 v127, v124, v120
	v_and_b32_e32 v121, 0xffff0000, v130
	v_lshlrev_b32_e32 v128, 16, v132
	v_and_b32_e32 v129, 0xffff0000, v132
	ds_bpermute_b32 v132, v124, v121
	s_waitcnt lgkmcnt(0)
	v_mul_f32_e32 v127, v89, v127
	v_cndmask_b32_e64 v127, v127, -v127, s[6:7]
	v_lshlrev_b32_e32 v125, 16, v131
	v_fmac_f32_e32 v127, v88, v120
	v_cndmask_b32_e64 v120, v120, v127, s[4:5]
	v_mul_f32_e32 v127, v91, v132
	ds_bpermute_b32 v132, v124, v125
	v_cndmask_b32_e64 v127, v127, -v127, s[6:7]
	v_and_b32_e32 v126, 0xffff0000, v131
	v_fmac_f32_e32 v127, v90, v121
	v_cndmask_b32_e64 v121, v121, v127, s[4:5]
	s_waitcnt lgkmcnt(0)
; __device__ __forceinline__ unsigned cvt_pk_bf16(float lo, float hi) { unsigned r; asm volatile("v_cvt_pk_bf16_f32 %0, %1, %2" : "=v"(r) : "v"(lo), "v"(hi)); return r; }
; __device__ __forceinline__ float shx(float v, int m, int lane) { return __int_as_float(__builtin_amdgcn_ds_bpermute((lane ^ m) << 2, __float_as_int(v))); }
; #define DPPF(v, ctrl) __int_as_float(__builtin_amdgcn_update_dpp(0, __float_as_int(v), (ctrl), 0xf, 0xf, false))
; template <bool NORM, int ROT> __device__ __forceinline__ void rope_chunk(bf16_t* p, const u32x4 w, const f32x4 (&tb)[4], const float* g, float sc, int lane) {
;     ...
;     constexpr int HALFL = ROT / 16;
;     const bool rot = (ROT == 128) || (j < 8); const bool first = (j & HALFL) == 0;
;     float o[8];
; #pragma unroll
;     for (int q = 0; q < 8; ++q) {
;         const float other = (ROT == 128) ? DPPF(x[q], 0x128)   : shx(x[q], HALFL, lane);
;         const float cs = tb[q >> 1][(q & 1) * 2], sn = tb[q >> 1][(q & 1) * 2 + 1];
;         const float r = first ? (x[q] * cs - other * sn) : (x[q] * cs + other * sn);
;         o[q] = (rot ? r : x[q]) * sc;
;     }
;     u32x4 ow; ow.x = cvt_pk_bf16(o[0], o[1]); ow.y = cvt_pk_bf16(o[2], o[3]); ow.z = cvt_pk_bf16(o[4], o[5]); ow.w = cvt_pk_bf16(o[6], o[7]);
;     *(u32x4*)(p + lane * 8) = ow;
	v_mul_f32_e32 v127, v93, v132
	ds_bpermute_b32 v132, v124, v126
	v_cndmask_b32_e64 v127, v127, -v127, s[6:7]
	v_fmac_f32_e32 v127, v92, v125
	v_cndmask_b32_e64 v125, v125, v127, s[4:5]
	v_lshlrev_b32_e32 v130, 16, v133
	s_waitcnt lgkmcnt(0)
	v_mul_f32_e32 v127, v95, v132
	ds_bpermute_b32 v132, v124, v128
	v_cndmask_b32_e64 v127, v127, -v127, s[6:7]
	v_fmac_f32_e32 v127, v94, v126
	v_cndmask_b32_e64 v126, v126, v127, s[4:5]
	v_mul_f32_e32 v127, 0x3db504f3, v126
	s_waitcnt lgkmcnt(0)
	v_mul_f32_e32 v126, v85, v132
	ds_bpermute_b32 v132, v124, v129
	v_cndmask_b32_e64 v126, v126, -v126, s[6:7]
	v_fmac_f32_e32 v126, v84, v128
	v_cndmask_b32_e64 v126, v128, v126, s[4:5]
	v_mul_f32_e32 v128, 0x3db504f3, v126
	s_waitcnt lgkmcnt(0)
	v_mul_f32_e32 v126, v87, v132
	ds_bpermute_b32 v132, v124, v130
	v_cndmask_b32_e64 v126, v126, -v126, s[6:7]
	v_fmac_f32_e32 v126, v86, v129
	v_and_b32_e32 v131, 0xffff0000, v133
	v_cndmask_b32_e64 v126, v129, v126, s[4:5]
	v_mul_f32_e32 v129, 0x3db504f3, v126
	s_waitcnt lgkmcnt(0)
	v_mul_f32_e32 v126, v77, v132
	ds_bpermute_b32 v132, v124, v131
	v_cndmask_b32_e64 v126, v126, -v126, s[6:7]
	v_fmac_f32_e32 v126, v76, v130
	v_cndmask_b32_e64 v126, v130, v126, s[4:5]
	v_mul_f32_e32 v130, 0x3db504f3, v126
	s_waitcnt lgkmcnt(0)
	v_mul_f32_e32 v126, v79, v132
	v_cndmask_b32_e64 v126, v126, -v126, s[6:7]
	v_fmac_f32_e32 v126, v78, v131
	v_cndmask_b32_e64 v126, v131, v126, s[4:5]
	v_mul_f32_e32 v120, 0x3db504f3, v120
	v_mul_f32_e32 v121, 0x3db504f3, v121
	v_mul_f32_e32 v125, 0x3db504f3, v125
	v_mul_f32_e32 v131, 0x3db504f3, v126
	v_cvt_pk_bf16_f32 v126, v120, v121
	v_cvt_pk_bf16_f32 v127, v125, v127
	v_cvt_pk_bf16_f32 v128, v128, v129
	v_cvt_pk_bf16_f32 v129, v130, v131
	flat_store_dwordx4 v[118:119], v[126:129]
	v_lshlrev_b32_e32 v118, 16, v100
	ds_bpermute_b32 v120, v124, v118
	v_and_b32_e32 v100, 0xffff0000, v100
	ds_bpermute_b32 v126, v124, v100
	v_lshlrev_b32_e32 v119, 16, v101
	v_and_b32_e32 v101, 0xffff0000, v101
	s_waitcnt lgkmcnt(0)
	v_mul_f32_e32 v120, v89, v120
	v_cndmask_b32_e64 v120, v120, -v120, s[6:7]
	v_fmac_f32_e32 v120, v88, v118
	v_cndmask_b32_e64 v118, v118, v120, s[4:5]
	v_mul_f32_e32 v120, v91, v126
	ds_bpermute_b32 v126, v124, v119
	v_cndmask_b32_e64 v120, v120, -v120, s[6:7]
	v_fmac_f32_e32 v120, v90, v100
	v_cndmask_b32_e64 v100, v100, v120, s[4:5]
	v_lshlrev_b32_e32 v121, 16, v102
	s_waitcnt lgkmcnt(0)
	v_mul_f32_e32 v120, v93, v126
	ds_bpermute_b32 v126, v124, v101
	v_cndmask_b32_e64 v120, v120, -v120, s[6:7]
	v_fmac_f32_e32 v120, v92, v119
	v_cndmask_b32_e64 v119, v119, v120, s[4:5]
	v_and_b32_e32 v102, 0xffff0000, v102
	s_waitcnt lgkmcnt(0)
	v_mul_f32_e32 v120, v95, v126
	ds_bpermute_b32 v126, v124, v121
	v_cndmask_b32_e64 v120, v120, -v120, s[6:7]
	v_fmac_f32_e32 v120, v94, v101
	v_cndmask_b32_e64 v101, v101, v120, s[4:5]
	v_lshlrev_b32_e32 v125, 16, v103
	s_waitcnt lgkmcnt(0)
	v_mul_f32_e32 v120, v85, v126
	ds_bpermute_b32 v126, v124, v102
	v_cndmask_b32_e64 v120, v120, -v120, s[6:7]
	v_fmac_f32_e32 v120, v84, v121
	v_cndmask_b32_e64 v120, v121, v120, s[4:5]
	v_and_b32_e32 v103, 0xffff0000, v103
	s_waitcnt lgkmcnt(0)
	v_mul_f32_e32 v121, v87, v126
	ds_bpermute_b32 v126, v124, v125
	v_cndmask_b32_e64 v121, v121, -v121, s[6:7]
	v_fmac_f32_e32 v121, v86, v102
	v_cndmask_b32_e64 v102, v102, v121, s[4:5]
	v_mul_f32_e32 v100, 0x3db504f3, v100
	s_waitcnt lgkmcnt(0)
	v_mul_f32_e32 v121, v77, v126
	ds_bpermute_b32 v126, v124, v103
	v_cndmask_b32_e64 v121, v121, -v121, s[6:7]
	v_fmac_f32_e32 v121, v76, v125
	v_cndmask_b32_e64 v121, v125, v121, s[4:5]
	v_mul_f32_e32 v118, 0x3db504f3, v118
	s_waitcnt lgkmcnt(0)
	v_mul_f32_e32 v125, v79, v126
	v_cndmask_b32_e64 v125, v125, -v125, s[6:7]
	v_fmac_f32_e32 v125, v78, v103
	v_cndmask_b32_e64 v103, v103, v125, s[4:5]
	v_mul_f32_e32 v101, 0x3db504f3, v101
	v_mul_f32_e32 v102, 0x3db504f3, v102
	v_mul_f32_e32 v103, 0x3db504f3, v103
	v_cvt_pk_bf16_f32 v100, v118, v100
	v_mul_f32_e32 v119, 0x3db504f3, v119
	v_mul_f32_e32 v120, 0x3db504f3, v120
	v_mul_f32_e32 v121, 0x3db504f3, v121
	v_cvt_pk_bf16_f32 v101, v119, v101
	v_cvt_pk_bf16_f32 v102, v120, v102
	v_cvt_pk_bf16_f32 v103, v121, v103
	flat_store_dwordx4 v[116:117], v[100:103]
	v_lshlrev_b32_e32 v116, 16, v99
	v_and_b32_e32 v99, 0xffff0000, v99
	v_lshlrev_b32_e32 v100, 16, v96
	ds_bpermute_b32 v102, v124, v100
	v_and_b32_e32 v96, 0xffff0000, v96
	v_lshlrev_b32_e32 v101, 16, v97
	v_lshlrev_b32_e32 v103, 16, v98
	v_and_b32_e32 v98, 0xffff0000, v98
	s_waitcnt lgkmcnt(0)
	v_mul_f32_e32 v89, v89, v102
	ds_bpermute_b32 v102, v124, v96
	v_cndmask_b32_e64 v89, v89, -v89, s[6:7]
	v_fmac_f32_e32 v89, v88, v100
	v_cndmask_b32_e64 v88, v100, v89, s[4:5]
	v_and_b32_e32 v97, 0xffff0000, v97
	s_waitcnt lgkmcnt(0)
	v_mul_f32_e32 v89, v91, v102
	ds_bpermute_b32 v91, v124, v101
	v_cndmask_b32_e64 v89, v89, -v89, s[6:7]
	v_fmac_f32_e32 v89, v90, v96
	v_cndmask_b32_e64 v89, v96, v89, s[4:5]
	v_mul_f32_e32 v88, 0x3db504f3, v88
	s_waitcnt lgkmcnt(0)
	v_mul_f32_e32 v90, v93, v91
	v_cndmask_b32_e64 v90, v90, -v90, s[6:7]
	v_fmac_f32_e32 v90, v92, v101
	ds_bpermute_b32 v92, v124, v103
	ds_bpermute_b32 v91, v124, v97
	v_mul_f32_e32 v89, 0x3db504f3, v89
	v_cndmask_b32_e64 v90, v101, v90, s[4:5]
	v_mul_f32_e32 v90, 0x3db504f3, v90
	s_waitcnt lgkmcnt(0)
	v_mul_f32_e32 v85, v85, v92
	ds_bpermute_b32 v92, v124, v98
	v_cndmask_b32_e64 v85, v85, -v85, s[6:7]
	v_fmac_f32_e32 v85, v84, v103
	v_cndmask_b32_e64 v84, v103, v85, s[4:5]
	v_mul_f32_e32 v91, v95, v91
	s_waitcnt lgkmcnt(0)
	v_mul_f32_e32 v85, v87, v92
	ds_bpermute_b32 v87, v124, v116
	v_cndmask_b32_e64 v85, v85, -v85, s[6:7]
	v_fmac_f32_e32 v85, v86, v98
	ds_bpermute_b32 v86, v124, v99
	v_cndmask_b32_e64 v91, v91, -v91, s[6:7]
	s_waitcnt lgkmcnt(0)
; __device__ __forceinline__ unsigned cvt_pk_bf16(float lo, float hi) { unsigned r; asm volatile("v_cvt_pk_bf16_f32 %0, %1, %2" : "=v"(r) : "v"(lo), "v"(hi)); return r; }
; __device__ __forceinline__ float shx(float v, int m, int lane) { return __int_as_float(__builtin_amdgcn_ds_bpermute((lane ^ m) << 2, __float_as_int(v))); }
; #define DPPF(v, ctrl) __int_as_float(__builtin_amdgcn_update_dpp(0, __float_as_int(v), (ctrl), 0xf, 0xf, false))
; template <bool NORM, int ROT> __device__ __forceinline__ void rope_chunk(bf16_t* p, const u32x4 w, const f32x4 (&tb)[4], const float* g, float sc, int lane) {
;     ...
;     constexpr int HALFL = ROT / 16;
;     const bool rot = (ROT == 128) || (j < 8); const bool first = (j & HALFL) == 0;
;     float o[8];
; #pragma unroll
;     for (int q = 0; q < 8; ++q) {
;         const float other = (ROT == 128) ? DPPF(x[q], 0x128)   : shx(x[q], HALFL, lane);
;         const float cs = tb[q >> 1][(q & 1) * 2], sn = tb[q >> 1][(q & 1) * 2 + 1];
;         const float r = first ? (x[q] * cs - other * sn) : (x[q] * cs + other * sn);
;         o[q] = (rot ? r : x[q]) * sc;
;     }
;     u32x4 ow; ow.x = cvt_pk_bf16(o[0], o[1]); ow.y = cvt_pk_bf16(o[2], o[3]); ow.z = cvt_pk_bf16(o[4], o[5]); ow.w = cvt_pk_bf16(o[6], o[7]);
;     *(u32x4*)(p + lane * 8) = ow;
	v_mul_f32_e32 v77, v77, v87
	v_cndmask_b32_e64 v77, v77, -v77, s[6:7]
	v_fmac_f32_e32 v77, v76, v116
	v_cndmask_b32_e64 v76, v116, v77, s[4:5]
	v_mul_f32_e32 v87, 0x3db504f3, v76
	v_mul_f32_e32 v76, v79, v86
	v_cndmask_b32_e64 v76, v76, -v76, s[6:7]
	v_fmac_f32_e32 v76, v78, v99
	v_fmac_f32_e32 v91, v94, v97
	v_cndmask_b32_e64 v76, v99, v76, s[4:5]
	v_cndmask_b32_e64 v91, v97, v91, s[4:5]
	v_cndmask_b32_e64 v85, v98, v85, s[4:5]
	v_mul_f32_e32 v79, 0x3db504f3, v76
	v_cvt_pk_bf16_f32 v76, v88, v89
	v_mul_f32_e32 v91, 0x3db504f3, v91
	v_mul_f32_e32 v84, 0x3db504f3, v84
	v_mul_f32_e32 v85, 0x3db504f3, v85
	v_cvt_pk_bf16_f32 v77, v90, v91
	v_cvt_pk_bf16_f32 v78, v84, v85
	v_cvt_pk_bf16_f32 v79, v87, v79
	flat_store_dwordx4 v[114:115], v[76:79]
	v_lshlrev_b32_e32 v84, 16, v83
	v_and_b32_e32 v83, 0xffff0000, v83
	v_lshlrev_b32_e32 v76, 16, v80
	v_and_b32_e32 v77, 0xffff0000, v80
	ds_bpermute_b32 v80, v124, v76
	v_lshlrev_b32_e32 v78, 16, v81
	v_and_b32_e32 v79, 0xffff0000, v81
	v_lshlrev_b32_e32 v81, 16, v82
	v_and_b32_e32 v82, 0xffff0000, v82
	s_waitcnt lgkmcnt(0)
	v_mul_f32_e32 v73, v73, v80
	ds_bpermute_b32 v80, v124, v77
	v_cndmask_b32_e64 v73, v73, -v73, s[6:7]
	v_fmac_f32_e32 v73, v72, v76
	v_cndmask_b32_e64 v72, v76, v73, s[4:5]
	v_mul_f32_e32 v72, 0x3db504f3, v72
	s_waitcnt lgkmcnt(0)
	v_mul_f32_e32 v73, v75, v80
	ds_bpermute_b32 v75, v124, v78
	v_cndmask_b32_e64 v73, v73, -v73, s[6:7]
	v_fmac_f32_e32 v73, v74, v77
	ds_bpermute_b32 v74, v124, v79
	v_cndmask_b32_e64 v73, v77, v73, s[4:5]
	s_waitcnt lgkmcnt(0)
	v_mul_f32_e32 v69, v69, v75
	v_cndmask_b32_e64 v69, v69, -v69, s[6:7]
	v_fmac_f32_e32 v69, v68, v78
	v_cndmask_b32_e64 v68, v78, v69, s[4:5]
	v_mul_f32_e32 v69, v71, v74
	ds_bpermute_b32 v71, v124, v81
	v_cndmask_b32_e64 v69, v69, -v69, s[6:7]
	v_fmac_f32_e32 v69, v70, v79
	ds_bpermute_b32 v70, v124, v82
	v_mul_f32_e32 v73, 0x3db504f3, v73
	s_waitcnt lgkmcnt(0)
	v_mul_f32_e32 v65, v65, v71
	v_cndmask_b32_e64 v65, v65, -v65, s[6:7]
	v_fmac_f32_e32 v65, v64, v81
	v_cndmask_b32_e64 v64, v81, v65, s[4:5]
	v_mul_f32_e32 v65, v67, v70
	ds_bpermute_b32 v67, v124, v84
	v_cndmask_b32_e64 v65, v65, -v65, s[6:7]
	v_fmac_f32_e32 v65, v66, v82
	ds_bpermute_b32 v66, v124, v83
	v_cndmask_b32_e64 v69, v79, v69, s[4:5]
	s_waitcnt lgkmcnt(0)
	v_mul_f32_e32 v57, v57, v67
	v_cndmask_b32_e64 v57, v57, -v57, s[6:7]
	v_fmac_f32_e32 v57, v56, v84
	v_cndmask_b32_e64 v56, v84, v57, s[4:5]
	v_mul_f32_e32 v67, 0x3db504f3, v56
	v_mul_f32_e32 v56, v59, v66
	v_cndmask_b32_e64 v56, v56, -v56, s[6:7]
	v_fmac_f32_e32 v56, v58, v83
	v_cndmask_b32_e64 v56, v83, v56, s[4:5]
	v_cndmask_b32_e64 v65, v82, v65, s[4:5]
	v_mul_f32_e32 v59, 0x3db504f3, v56
	v_cvt_pk_bf16_f32 v56, v72, v73
	v_mul_f32_e32 v68, 0x3db504f3, v68
	v_mul_f32_e32 v69, 0x3db504f3, v69
	v_mul_f32_e32 v64, 0x3db504f3, v64
	v_mul_f32_e32 v65, 0x3db504f3, v65
	v_cvt_pk_bf16_f32 v57, v68, v69
	v_cvt_pk_bf16_f32 v58, v64, v65
	v_cvt_pk_bf16_f32 v59, v67, v59
	flat_store_dwordx4 v[112:113], v[56:59]
	v_lshlrev_b32_e32 v64, 16, v63
	v_and_b32_e32 v63, 0xffff0000, v63
	v_lshlrev_b32_e32 v56, 16, v60
	v_and_b32_e32 v57, 0xffff0000, v60
	ds_bpermute_b32 v60, v124, v56
	v_lshlrev_b32_e32 v58, 16, v61
	v_and_b32_e32 v59, 0xffff0000, v61
	v_lshlrev_b32_e32 v61, 16, v62
	v_and_b32_e32 v62, 0xffff0000, v62
	s_waitcnt lgkmcnt(0)
	v_mul_f32_e32 v53, v53, v60
	ds_bpermute_b32 v60, v124, v57
	v_cndmask_b32_e64 v53, v53, -v53, s[6:7]
	v_fmac_f32_e32 v53, v52, v56
	v_cndmask_b32_e64 v52, v56, v53, s[4:5]
	v_mul_f32_e32 v52, 0x3db504f3, v52
	s_waitcnt lgkmcnt(0)
	v_mul_f32_e32 v53, v55, v60
	ds_bpermute_b32 v55, v124, v58
	v_cndmask_b32_e64 v53, v53, -v53, s[6:7]
	v_fmac_f32_e32 v53, v54, v57
	ds_bpermute_b32 v54, v124, v59
	v_cndmask_b32_e64 v53, v57, v53, s[4:5]
	s_waitcnt lgkmcnt(0)
	v_mul_f32_e32 v49, v49, v55
	v_cndmask_b32_e64 v49, v49, -v49, s[6:7]
	v_fmac_f32_e32 v49, v48, v58
	v_cndmask_b32_e64 v48, v58, v49, s[4:5]
	v_mul_f32_e32 v49, v51, v54
	ds_bpermute_b32 v51, v124, v61
	v_cndmask_b32_e64 v49, v49, -v49, s[6:7]
	v_fmac_f32_e32 v49, v50, v59
	ds_bpermute_b32 v50, v124, v62
	v_mul_f32_e32 v53, 0x3db504f3, v53
	s_waitcnt lgkmcnt(0)
	v_mul_f32_e32 v45, v45, v51
	v_cndmask_b32_e64 v45, v45, -v45, s[6:7]
	v_fmac_f32_e32 v45, v44, v61
	v_cndmask_b32_e64 v44, v61, v45, s[4:5]
	v_mul_f32_e32 v45, v47, v50
	ds_bpermute_b32 v47, v124, v64
	v_cndmask_b32_e64 v45, v45, -v45, s[6:7]
	v_fmac_f32_e32 v45, v46, v62
	ds_bpermute_b32 v46, v124, v63
	v_cndmask_b32_e64 v49, v59, v49, s[4:5]
	s_waitcnt lgkmcnt(0)
	v_mul_f32_e32 v37, v37, v47
	v_cndmask_b32_e64 v37, v37, -v37, s[6:7]
	v_fmac_f32_e32 v37, v36, v64
	v_cndmask_b32_e64 v36, v64, v37, s[4:5]
	v_mul_f32_e32 v47, 0x3db504f3, v36
	v_mul_f32_e32 v36, v39, v46
	v_cndmask_b32_e64 v36, v36, -v36, s[6:7]
	v_fmac_f32_e32 v36, v38, v63
	v_cndmask_b32_e64 v36, v63, v36, s[4:5]
	v_cndmask_b32_e64 v45, v62, v45, s[4:5]
	v_mul_f32_e32 v39, 0x3db504f3, v36
	v_cvt_pk_bf16_f32 v36, v52, v53
	v_mul_f32_e32 v48, 0x3db504f3, v48
	v_mul_f32_e32 v49, 0x3db504f3, v49
	v_mul_f32_e32 v44, 0x3db504f3, v44
	v_mul_f32_e32 v45, 0x3db504f3, v45
	v_cvt_pk_bf16_f32 v37, v48, v49
	v_cvt_pk_bf16_f32 v38, v44, v45
	v_cvt_pk_bf16_f32 v39, v47, v39
	flat_store_dwordx4 v[110:111], v[36:39]
	v_lshlrev_b32_e32 v44, 16, v43
	v_and_b32_e32 v43, 0xffff0000, v43
	v_lshlrev_b32_e32 v36, 16, v40
	v_and_b32_e32 v37, 0xffff0000, v40
	ds_bpermute_b32 v40, v124, v36
	v_lshlrev_b32_e32 v38, 16, v41
	v_and_b32_e32 v39, 0xffff0000, v41
	v_lshlrev_b32_e32 v41, 16, v42
	v_and_b32_e32 v42, 0xffff0000, v42
	s_waitcnt lgkmcnt(0)
; __device__ __forceinline__ unsigned cvt_pk_bf16(float lo, float hi) { unsigned r; asm volatile("v_cvt_pk_bf16_f32 %0, %1, %2" : "=v"(r) : "v"(lo), "v"(hi)); return r; }
; __device__ __forceinline__ float shx(float v, int m, int lane) { return __int_as_float(__builtin_amdgcn_ds_bpermute((lane ^ m) << 2, __float_as_int(v))); }
; #define DPPF(v, ctrl) __int_as_float(__builtin_amdgcn_update_dpp(0, __float_as_int(v), (ctrl), 0xf, 0xf, false))
; template <bool NORM, int ROT> __device__ __forceinline__ void rope_chunk(bf16_t* p, const u32x4 w, const f32x4 (&tb)[4], const float* g, float sc, int lane) {
;     ...
;     for (int q = 0; q < 8; ++q) {
;         const float other = (ROT == 128) ? DPPF(x[q], 0x128)   : shx(x[q], HALFL, lane);
;         const float cs = tb[q >> 1][(q & 1) * 2], sn = tb[q >> 1][(q & 1) * 2 + 1];
;         const float r = first ? (x[q] * cs - other * sn) : (x[q] * cs + other * sn);
;         o[q] = (rot ? r : x[q]) * sc;
;     }
;     u32x4 ow; ow.x = cvt_pk_bf16(o[0], o[1]); ow.y = cvt_pk_bf16(o[2], o[3]); ow.z = cvt_pk_bf16(o[4], o[5]); ow.w = cvt_pk_bf16(o[6], o[7]);
;     *(u32x4*)(p + lane * 8) = ow;
; }
; template <bool NORM, int ROT, bool PERTOK> __device__ __forceinline__ void rope_pass(bf16_t* base, int nchunks, const float* g, const float* tab, float sc, int gw, int NGW, int lane) {
;     constexpr int NB = 8, HALFL = ROT / 16; const int j = lane & 15;
;     for (int it0 = gw * NB; it0 < nchunks; it0 += NGW * NB) {
; __device__ __forceinline__ void post_proj(const Args& A, int gw, int NGW, int lane) {
;     ...
;     rope_pass<true, 64, false>((bf16_t*)(ws + WS_IK), T / 4, A.idx_k_norm_g, R2, 1.f, gw, NGW, lane);
	v_mul_f32_e32 v33, v33, v40
	ds_bpermute_b32 v40, v124, v37
	v_cndmask_b32_e64 v33, v33, -v33, s[6:7]
	v_fmac_f32_e32 v33, v32, v36
	v_cndmask_b32_e64 v32, v36, v33, s[4:5]
	v_mul_f32_e32 v32, 0x3db504f3, v32
	s_waitcnt lgkmcnt(0)
	v_mul_f32_e32 v33, v35, v40
	ds_bpermute_b32 v35, v124, v38
	v_cndmask_b32_e64 v33, v33, -v33, s[6:7]
	v_fmac_f32_e32 v33, v34, v37
	ds_bpermute_b32 v34, v124, v39
	v_cndmask_b32_e64 v33, v37, v33, s[4:5]
	s_waitcnt lgkmcnt(0)
	v_mul_f32_e32 v29, v29, v35
	v_cndmask_b32_e64 v29, v29, -v29, s[6:7]
	v_fmac_f32_e32 v29, v28, v38
	v_cndmask_b32_e64 v28, v38, v29, s[4:5]
	v_mul_f32_e32 v29, v31, v34
	ds_bpermute_b32 v31, v124, v41
	v_cndmask_b32_e64 v29, v29, -v29, s[6:7]
	v_fmac_f32_e32 v29, v30, v39
	ds_bpermute_b32 v30, v124, v42
	v_mul_f32_e32 v33, 0x3db504f3, v33
	s_waitcnt lgkmcnt(0)
	v_mul_f32_e32 v25, v25, v31
	v_cndmask_b32_e64 v25, v25, -v25, s[6:7]
	v_fmac_f32_e32 v25, v24, v41
	v_cndmask_b32_e64 v24, v41, v25, s[4:5]
	v_mul_f32_e32 v25, v27, v30
	ds_bpermute_b32 v27, v124, v44
	v_cndmask_b32_e64 v25, v25, -v25, s[6:7]
	v_fmac_f32_e32 v25, v26, v42
	ds_bpermute_b32 v26, v124, v43
	v_cndmask_b32_e64 v29, v39, v29, s[4:5]
	s_waitcnt lgkmcnt(0)
	v_mul_f32_e32 v21, v21, v27
	v_cndmask_b32_e64 v21, v21, -v21, s[6:7]
	v_fmac_f32_e32 v21, v20, v44
	v_cndmask_b32_e64 v20, v44, v21, s[4:5]
	v_mul_f32_e32 v27, 0x3db504f3, v20
	v_mul_f32_e32 v20, v23, v26
	v_cndmask_b32_e64 v20, v20, -v20, s[6:7]
	v_fmac_f32_e32 v20, v22, v43
	v_cndmask_b32_e64 v20, v43, v20, s[4:5]
	v_cndmask_b32_e64 v25, v42, v25, s[4:5]
	v_mul_f32_e32 v23, 0x3db504f3, v20
	v_cvt_pk_bf16_f32 v20, v32, v33
	v_mul_f32_e32 v28, 0x3db504f3, v28
	v_mul_f32_e32 v29, 0x3db504f3, v29
	v_mul_f32_e32 v24, 0x3db504f3, v24
	v_mul_f32_e32 v25, 0x3db504f3, v25
	v_cvt_pk_bf16_f32 v21, v28, v29
	v_cvt_pk_bf16_f32 v22, v24, v25
	v_cvt_pk_bf16_f32 v23, v27, v23
	flat_store_dwordx4 v[108:109], v[20:23]
	v_lshlrev_b32_e32 v24, 16, v7
	v_and_b32_e32 v7, 0xffff0000, v7
	v_lshlrev_b32_e32 v20, 16, v4
	ds_bpermute_b32 v22, v124, v20
	v_and_b32_e32 v4, 0xffff0000, v4
	v_lshlrev_b32_e32 v21, 16, v5
	v_and_b32_e32 v5, 0xffff0000, v5
	v_lshlrev_b32_e32 v23, 16, v6
	s_waitcnt lgkmcnt(0)
	v_mul_f32_e32 v17, v17, v22
	ds_bpermute_b32 v22, v124, v4
	v_cndmask_b32_e64 v17, v17, -v17, s[6:7]
	v_fmac_f32_e32 v17, v16, v20
	v_cndmask_b32_e64 v16, v20, v17, s[4:5]
	v_and_b32_e32 v6, 0xffff0000, v6
	s_waitcnt lgkmcnt(0)
	v_mul_f32_e32 v17, v19, v22
	ds_bpermute_b32 v19, v124, v21
	v_cndmask_b32_e64 v17, v17, -v17, s[6:7]
	v_fmac_f32_e32 v17, v18, v4
	v_cndmask_b32_e64 v4, v4, v17, s[4:5]
	ds_bpermute_b32 v17, v124, v5
	s_waitcnt lgkmcnt(0)
	v_mul_f32_e32 v13, v13, v19
	v_cndmask_b32_e64 v13, v13, -v13, s[6:7]
	v_fmac_f32_e32 v13, v12, v21
	v_cndmask_b32_e64 v12, v21, v13, s[4:5]
	v_mul_f32_e32 v13, v15, v17
	ds_bpermute_b32 v15, v124, v23
	v_cndmask_b32_e64 v13, v13, -v13, s[6:7]
	v_fmac_f32_e32 v13, v14, v5
	v_cndmask_b32_e64 v5, v5, v13, s[4:5]
	ds_bpermute_b32 v13, v124, v6
	s_waitcnt lgkmcnt(0)
	v_mul_f32_e32 v9, v9, v15
	v_cndmask_b32_e64 v9, v9, -v9, s[6:7]
	v_fmac_f32_e32 v9, v8, v23
	v_cndmask_b32_e64 v8, v23, v9, s[4:5]
	v_mul_f32_e32 v9, v11, v13
	ds_bpermute_b32 v11, v124, v24
	v_cndmask_b32_e64 v9, v9, -v9, s[6:7]
	v_fmac_f32_e32 v9, v10, v6
	v_cndmask_b32_e64 v6, v6, v9, s[4:5]
	ds_bpermute_b32 v9, v124, v7
	s_waitcnt lgkmcnt(0)
	v_mul_f32_e32 v1, v1, v11
	v_cndmask_b32_e64 v1, v1, -v1, s[6:7]
	v_fmac_f32_e32 v1, v0, v24
	v_cndmask_b32_e64 v0, v24, v1, s[4:5]
	v_mul_f32_e32 v10, 0x3db504f3, v0
	v_mul_f32_e32 v0, v3, v9
	v_cndmask_b32_e64 v0, v0, -v0, s[6:7]
	v_fmac_f32_e32 v0, v2, v7
	v_cndmask_b32_e64 v0, v7, v0, s[4:5]
	v_mul_f32_e32 v3, 0x3db504f3, v0
	v_mul_f32_e32 v16, 0x3db504f3, v16
	v_mul_f32_e32 v4, 0x3db504f3, v4
	v_mul_f32_e32 v12, 0x3db504f3, v12
	v_mul_f32_e32 v5, 0x3db504f3, v5
	v_mul_f32_e32 v8, 0x3db504f3, v8
	v_mul_f32_e32 v6, 0x3db504f3, v6
	v_cvt_pk_bf16_f32 v0, v16, v4
	v_cvt_pk_bf16_f32 v1, v12, v5
	v_cvt_pk_bf16_f32 v2, v8, v6
	v_cvt_pk_bf16_f32 v3, v10, v3
	flat_store_dwordx4 v[106:107], v[0:3]
	v_lshl_add_u64 v[106:107], v[106:107], 0, s[22:23]
	s_cbranch_scc1 .LBB0_1077
.LBB0_1078:
	s_cmpk_gt_i32 s0, 0xff
	s_cbranch_scc1 .LBB0_1081
	s_lshl_b32 s14, s0, 3
	v_and_b32_e32 v0, 0xc0, v180
	v_mov_b32_e32 v1, 0
	v_and_b32_e32 v2, 15, v179
	v_readlane_b32 s1, v255, 3
	v_lshl_add_u64 v[158:159], s[16:17], 0, v[0:1]
	v_lshlrev_b32_e32 v0, 5, v2
	s_lshl_b32 s0, s2, 8
	s_lshl_b32 s1, s1, 5
	s_ashr_i32 s15, s14, 31
	v_lshl_add_u64 v[160:161], s[12:13], 0, v[0:1]
	s_lshl_b32 s12, s44, 6
	s_add_i32 s0, s0, s1
	s_lshl_b32 s1, s44, 8
	s_lshl_b64 s[16:17], s[14:15], 10
	s_add_u32 s10, s10, s16
	v_ashrrev_i32_e32 v157, 31, v156
	s_addc_u32 s11, s11, s17
	v_lshl_add_u64 v[0:1], v[156:157], 1, s[10:11]
	s_mov_b64 s[10:11], 0xa01c00
	s_ashr_i32 s13, s12, 31
	v_cmp_gt_u32_e64 s[4:5], 8, v2
	v_cmp_eq_u32_e64 s[6:7], 0, v122
	v_xor_b32_e32 v176, 16, v123
	v_lshl_add_u64 v[156:157], v[0:1], 0, s[10:11]
	s_lshl_b64 s[10:11], s[12:13], 10
	s_movk_i32 s3, 0xe800
	s_movk_i32 s13, 0xec00
	s_movk_i32 s15, 0xf000
	s_movk_i32 s16, 0xf400
	s_movk_i32 s17, 0xf800
	s_movk_i32 s18, 0xfc00
	v_mov_b32_e32 v177, 0x358637bd
	s_mov_b32 s19, 0x800000
; __device__ __forceinline__ float row16_sum(float x) { x += DPPF(x, 0xB1); x += DPPF(x, 0x4E); x += DPPF(x, 0x141); x += DPPF(x, 0x140); return x; }
; template <bool NORM, int ROT> __device__ __forceinline__ void rope_chunk(bf16_t* p, const u32x4 w, const f32x4 (&tb)[4], const float* g, float sc, int lane) {
;     ...
;         float ss = 0.f;
; #pragma unroll
;         for (int q = 0; q < 8; ++q) ss += x[q] * x[q];
;         ss = row16_sum(ss);
;         const float rstd = rsqrtf(ss * (1.f / 128.f) + EPS);
;         const f32x4 g0 = *(const f32x4*)(g + j * 8), g1 = *(const f32x4*)(g + j * 8 + 4);
; #pragma unroll
;         for (int q = 0; q < 4; ++q) { x[q] *= rstd * g0[q]; x[4 + q] *= rstd * g1[q]; }
; template <bool NORM, int ROT, bool PERTOK> __device__ __forceinline__ void rope_pass(bf16_t* base, int nchunks, const float* g, const float* tab, float sc, int gw, int NGW, int lane) {
;     ...
;     for (int it0 = gw * NB; it0 < nchunks; it0 += NGW * NB) {
;         u32x4 w[NB]; f32x4 tb[NB][4];
; #pragma unroll
;         for (int k = 0; k < NB; ++k) { const int it = it0 + k;
;             w[k] = *(const u32x4*)(base + (size_t)it * 512 + lane * 8);
;             const int pos = PERTOK ? ((it >> 2) & 8191) : (((it * 4) & 8191) + (lane >> 4));
;             const float* tp = tab + (size_t)pos * ROT + (j & (HALFL - 1)) * 16;
; #pragma unroll
;             for (int q = 0; q < 4; ++q) tb[k][q] = *(const f32x4*)(tp + q * 4); }
.LBB0_1080:
	v_add_co_u32_e32 v174, vcc, 0xffffe400, v156
	s_and_b32 s20, s0, 0x1fe0
	s_nop 0
	v_addc_co_u32_e32 v175, vcc, -1, v157, vcc
	flat_load_dwordx4 v[0:3], v[174:175]
	v_add_u32_e32 v4, s20, v178
	v_ashrrev_i32_e32 v5, 31, v4
	v_lshlrev_b64 v[4:5], 8, v[4:5]
	s_add_i32 s20, s0, 4
	v_lshl_add_u64 v[4:5], v[158:159], 0, v[4:5]
	s_and_b32 s20, s20, 0x1fe4
	flat_load_dwordx4 v[152:155], v[4:5]
	flat_load_dwordx4 v[148:151], v[4:5] offset:16
	flat_load_dwordx4 v[144:147], v[4:5] offset:32
	flat_load_dwordx4 v[140:143], v[4:5] offset:48
	v_add_u32_e32 v4, s20, v178
	v_ashrrev_i32_e32 v5, 31, v4
	v_add_co_u32_e32 v172, vcc, s3, v156
	v_lshlrev_b64 v[4:5], 8, v[4:5]
	s_add_i32 s20, s0, 8
	v_addc_co_u32_e32 v173, vcc, -1, v157, vcc
	v_lshl_add_u64 v[4:5], v[158:159], 0, v[4:5]
	s_and_b32 s20, s20, 0x1fe8
	flat_load_dwordx4 v[136:139], v[172:173]
	flat_load_dwordx4 v[132:135], v[4:5]
	flat_load_dwordx4 v[128:131], v[4:5] offset:16
	flat_load_dwordx4 v[124:127], v[4:5] offset:32
	flat_load_dwordx4 v[120:123], v[4:5] offset:48
	v_add_u32_e32 v4, s20, v178
	v_ashrrev_i32_e32 v5, 31, v4
	v_add_co_u32_e32 v170, vcc, s13, v156
	v_lshlrev_b64 v[4:5], 8, v[4:5]
	s_add_i32 s20, s0, 12
	v_addc_co_u32_e32 v171, vcc, -1, v157, vcc
	v_lshl_add_u64 v[4:5], v[158:159], 0, v[4:5]
	s_and_b32 s20, s20, 0x1fec
	flat_load_dwordx4 v[116:119], v[170:171]
	flat_load_dwordx4 v[112:115], v[4:5]
	flat_load_dwordx4 v[108:111], v[4:5] offset:16
	flat_load_dwordx4 v[104:107], v[4:5] offset:32
	flat_load_dwordx4 v[100:103], v[4:5] offset:48
	v_add_u32_e32 v4, s20, v178
	v_ashrrev_i32_e32 v5, 31, v4
	v_add_co_u32_e32 v168, vcc, s15, v156
	v_lshlrev_b64 v[4:5], 8, v[4:5]
	s_nop 0
	v_addc_co_u32_e32 v169, vcc, -1, v157, vcc
	v_lshl_add_u64 v[4:5], v[158:159], 0, v[4:5]
	flat_load_dwordx4 v[96:99], v[168:169]
	flat_load_dwordx4 v[92:95], v[4:5]
	flat_load_dwordx4 v[88:91], v[4:5] offset:16
	flat_load_dwordx4 v[84:87], v[4:5] offset:32
	flat_load_dwordx4 v[80:83], v[4:5] offset:48
	flat_load_dwordx4 v[180:183], v[160:161]
	s_add_i32 s20, s0, 16
	s_and_b32 s20, s20, 0x1ff0
	v_add_u32_e32 v4, s20, v178
	v_add_co_u32_e32 v166, vcc, s16, v156
	v_ashrrev_i32_e32 v5, 31, v4
	s_nop 0
	v_addc_co_u32_e32 v167, vcc, -1, v157, vcc
	v_lshlrev_b64 v[4:5], 8, v[4:5]
	flat_load_dwordx4 v[60:63], v[166:167]
	v_lshl_add_u64 v[4:5], v[158:159], 0, v[4:5]
	flat_load_dwordx4 v[184:187], v[160:161] offset:16
	flat_load_dwordx4 v[76:79], v[4:5]
	flat_load_dwordx4 v[72:75], v[4:5] offset:16
	flat_load_dwordx4 v[68:71], v[4:5] offset:32
	flat_load_dwordx4 v[64:67], v[4:5] offset:48
	s_add_i32 s20, s0, 20
	s_and_b32 s20, s20, 0x1ff4
	v_add_u32_e32 v4, s20, v178
	v_ashrrev_i32_e32 v5, 31, v4
	v_add_co_u32_e32 v164, vcc, s17, v156
	v_lshlrev_b64 v[4:5], 8, v[4:5]
	s_add_i32 s20, s0, 24
	v_addc_co_u32_e32 v165, vcc, -1, v157, vcc
	v_lshl_add_u64 v[4:5], v[158:159], 0, v[4:5]
	s_and_b32 s20, s20, 0x1ff8
	flat_load_dwordx4 v[56:59], v[164:165]
	flat_load_dwordx4 v[52:55], v[4:5]
	flat_load_dwordx4 v[48:51], v[4:5] offset:16
	flat_load_dwordx4 v[44:47], v[4:5] offset:32
	flat_load_dwordx4 v[40:43], v[4:5] offset:48
	v_add_u32_e32 v4, s20, v178
	v_ashrrev_i32_e32 v5, 31, v4
	v_add_co_u32_e32 v162, vcc, s18, v156
	v_lshlrev_b64 v[4:5], 8, v[4:5]
	s_add_i32 s20, s0, 28
	v_addc_co_u32_e32 v163, vcc, -1, v157, vcc
	v_lshl_add_u64 v[4:5], v[158:159], 0, v[4:5]
	s_and_b32 s20, s20, 0x1ffc
	flat_load_dwordx4 v[36:39], v[162:163]
	flat_load_dwordx4 v[32:35], v[4:5]
	flat_load_dwordx4 v[28:31], v[4:5] offset:16
	flat_load_dwordx4 v[24:27], v[4:5] offset:32
	flat_load_dwordx4 v[20:23], v[4:5] offset:48
	flat_load_dwordx4 v[16:19], v[156:157]
	v_add_u32_e32 v4, s20, v178
	v_ashrrev_i32_e32 v5, 31, v4
	v_lshlrev_b64 v[4:5], 8, v[4:5]
	s_waitcnt vmcnt(0) lgkmcnt(0)
	v_and_b32_e32 v196, 0xffff0000, v0
	v_lshl_add_u64 v[188:189], v[158:159], 0, v[4:5]
	v_lshlrev_b32_e32 v179, 16, v0
	v_mul_f32_e32 v4, v196, v196
	v_and_b32_e32 v190, 0xffff0000, v1
	v_lshlrev_b32_e32 v191, 16, v1
	v_fmac_f32_e32 v4, v179, v179
	v_pk_mul_f32 v[0:1], v[190:191], v[190:191]
	v_and_b32_e32 v192, 0xffff0000, v2
	v_add_f32_e32 v1, v1, v4
	v_lshlrev_b32_e32 v193, 16, v2
	v_add_f32_e32 v4, v0, v1
	v_pk_mul_f32 v[0:1], v[192:193], v[192:193]
	v_and_b32_e32 v194, 0xffff0000, v3
	v_add_f32_e32 v1, v1, v4
	v_lshlrev_b32_e32 v195, 16, v3
	v_add_f32_e32 v2, v0, v1
	v_pk_mul_f32 v[0:1], v[194:195], v[194:195]
	s_add_i32 s14, s14, s12
	v_add_f32_e32 v1, v1, v2
	v_add_f32_e32 v0, v0, v1
	s_add_i32 s0, s0, s1
	s_cmpk_lt_i32 s14, 0x800
	v_add_f32_dpp v0, v0, v0 quad_perm:[1,0,3,2] row_mask:0xf bank_mask:0xf bound_ctrl:1
	s_nop 1
	v_add_f32_dpp v0, v0, v0 quad_perm:[2,3,0,1] row_mask:0xf bank_mask:0xf bound_ctrl:1
	s_nop 1
	v_add_f32_dpp v0, v0, v0 row_half_mirror row_mask:0xf bank_mask:0xf bound_ctrl:1
	s_nop 1
	v_add_f32_dpp v0, v0, v0 row_mirror row_mask:0xf bank_mask:0xf bound_ctrl:1
	v_fmamk_f32 v0, v0, 0x3c000000, v177
	v_mul_f32_e32 v1, 0x4b800000, v0
	v_cmp_gt_f32_e32 vcc, s19, v0
	s_nop 1
	v_cndmask_b32_e32 v0, v0, v1, vcc
	v_rsq_f32_e32 v197, v0
	flat_load_dwordx4 v[12:15], v[188:189]
	flat_load_dwordx4 v[8:11], v[188:189] offset:16
	flat_load_dwordx4 v[4:7], v[188:189] offset:32
	flat_load_dwordx4 v[0:3], v[188:189] offset:48
	v_mul_f32_e32 v188, 0x45800000, v197
	v_cndmask_b32_e32 v188, v197, v188, vcc
	v_mul_f32_e32 v180, v180, v188
	v_mul_f32_e32 v179, v180, v179
	v_mul_f32_e32 v180, v184, v188
	v_mul_f32_e32 v184, v185, v188
	v_mul_f32_e32 v185, v186, v188
	ds_bpermute_b32 v186, v176, v179
	v_mul_f32_e32 v181, v181, v188
	v_mul_f32_e32 v181, v181, v196
	v_mul_f32_e32 v182, v182, v188
	v_mul_f32_e32 v183, v183, v188
	v_mul_f32_e32 v187, v187, v188
	ds_bpermute_b32 v188, v176, v181
	s_waitcnt lgkmcnt(0)
; __device__ __forceinline__ unsigned cvt_pk_bf16(float lo, float hi) { unsigned r; asm volatile("v_cvt_pk_bf16_f32 %0, %1, %2" : "=v"(r) : "v"(lo), "v"(hi)); return r; }
; __device__ __forceinline__ float shx(float v, int m, int lane) { return __int_as_float(__builtin_amdgcn_ds_bpermute((lane ^ m) << 2, __float_as_int(v))); }
; #define DPPF(v, ctrl) __int_as_float(__builtin_amdgcn_update_dpp(0, __float_as_int(v), (ctrl), 0xf, 0xf, false))
; __device__ __forceinline__ float row16_sum(float x) { x += DPPF(x, 0xB1); x += DPPF(x, 0x4E); x += DPPF(x, 0x141); x += DPPF(x, 0x140); return x; }
; template <bool NORM, int ROT> __device__ __forceinline__ void rope_chunk(bf16_t* p, const u32x4 w, const f32x4 (&tb)[4], const float* g, float sc, int lane) {
;     ...
;         float ss = 0.f;
; #pragma unroll
;         for (int q = 0; q < 8; ++q) ss += x[q] * x[q];
;         ss = row16_sum(ss);
;         const float rstd = rsqrtf(ss * (1.f / 128.f) + EPS);
;         const f32x4 g0 = *(const f32x4*)(g + j * 8), g1 = *(const f32x4*)(g + j * 8 + 4);
; #pragma unroll
;         for (int q = 0; q < 4; ++q) { x[q] *= rstd * g0[q]; x[4 + q] *= rstd * g1[q]; }
;     }
;     constexpr int HALFL = ROT / 16;
;     const bool rot = (ROT == 128) || (j < 8); const bool first = (j & HALFL) == 0;
;     float o[8];
; #pragma unroll
;     for (int q = 0; q < 8; ++q) {
;         const float other = (ROT == 128) ? DPPF(x[q], 0x128)   : shx(x[q], HALFL, lane);
;         const float cs = tb[q >> 1][(q & 1) * 2], sn = tb[q >> 1][(q & 1) * 2 + 1];
;         const float r = first ? (x[q] * cs - other * sn) : (x[q] * cs + other * sn);
;         o[q] = (rot ? r : x[q]) * sc;
;     }
;     u32x4 ow; ow.x = cvt_pk_bf16(o[0], o[1]); ow.y = cvt_pk_bf16(o[2], o[3]); ow.z = cvt_pk_bf16(o[4], o[5]); ow.w = cvt_pk_bf16(o[6], o[7]);
;     *(u32x4*)(p + lane * 8) = ow;
	v_mul_f32_e32 v153, v153, v186
	v_cndmask_b32_e64 v153, v153, -v153, s[6:7]
	v_mul_f32_e32 v182, v182, v191
	v_fmac_f32_e32 v153, v152, v179
	v_cndmask_b32_e64 v152, v179, v153, s[4:5]
	v_mul_f32_e32 v153, v155, v188
	ds_bpermute_b32 v155, v176, v182
	v_mul_f32_e32 v183, v183, v190
	v_cndmask_b32_e64 v153, v153, -v153, s[6:7]
	v_fmac_f32_e32 v153, v154, v181
	ds_bpermute_b32 v154, v176, v183
	s_waitcnt lgkmcnt(0)
	v_mul_f32_e32 v149, v149, v155
	v_cndmask_b32_e64 v149, v149, -v149, s[6:7]
	v_mul_f32_e32 v180, v180, v193
	v_fmac_f32_e32 v149, v148, v182
	v_cndmask_b32_e64 v148, v182, v149, s[4:5]
	v_mul_f32_e32 v149, v151, v154
	ds_bpermute_b32 v151, v176, v180
	v_mul_f32_e32 v184, v184, v192
	v_cndmask_b32_e64 v149, v149, -v149, s[6:7]
	v_fmac_f32_e32 v149, v150, v183
	ds_bpermute_b32 v150, v176, v184
	s_waitcnt lgkmcnt(0)
	v_mul_f32_e32 v145, v145, v151
	v_cndmask_b32_e64 v145, v145, -v145, s[6:7]
	v_mul_f32_e32 v185, v185, v195
	v_fmac_f32_e32 v145, v144, v180
	v_cndmask_b32_e64 v144, v180, v145, s[4:5]
	v_mul_f32_e32 v145, v147, v150
	ds_bpermute_b32 v147, v176, v185
	v_mul_f32_e32 v187, v187, v194
	v_cndmask_b32_e64 v145, v145, -v145, s[6:7]
	v_fmac_f32_e32 v145, v146, v184
	ds_bpermute_b32 v146, v176, v187
	s_waitcnt lgkmcnt(0)
	v_mul_f32_e32 v141, v141, v147
	v_cndmask_b32_e64 v141, v141, -v141, s[6:7]
	v_fmac_f32_e32 v141, v140, v185
	v_cndmask_b32_e64 v153, v181, v153, s[4:5]
	v_mul_f32_e32 v140, v143, v146
	v_cndmask_b32_e64 v140, v140, -v140, s[6:7]
	v_fmac_f32_e32 v140, v142, v187
	v_cndmask_b32_e64 v143, v187, v140, s[4:5]
	v_cndmask_b32_e64 v149, v183, v149, s[4:5]
	v_cndmask_b32_e64 v145, v184, v145, s[4:5]
	v_cndmask_b32_e64 v147, v185, v141, s[4:5]
	v_cvt_pk_bf16_f32 v140, v152, v153
	v_cvt_pk_bf16_f32 v141, v148, v149
	v_cvt_pk_bf16_f32 v142, v144, v145
	v_cvt_pk_bf16_f32 v143, v147, v143
	flat_store_dwordx4 v[174:175], v[140:143]
	flat_load_dwordx4 v[140:143], v[160:161]
	s_nop 0
	flat_load_dwordx4 v[144:147], v[160:161] offset:16
	v_and_b32_e32 v153, 0xffff0000, v136
	v_lshlrev_b32_e32 v152, 16, v136
	v_mul_f32_e32 v150, v153, v153
	v_and_b32_e32 v136, 0xffff0000, v137
	v_lshlrev_b32_e32 v137, 16, v137
	v_fmac_f32_e32 v150, v152, v152
	v_pk_mul_f32 v[148:149], v[136:137], v[136:137]
	s_nop 0
	v_add_f32_e32 v149, v149, v150
	v_add_f32_e32 v154, v148, v149
	v_and_b32_e32 v148, 0xffff0000, v138
	v_lshlrev_b32_e32 v149, 16, v138
	v_pk_mul_f32 v[150:151], v[148:149], v[148:149]
	s_nop 0
	v_add_f32_e32 v138, v151, v154
	v_add_f32_e32 v154, v150, v138
	v_and_b32_e32 v138, 0xffff0000, v139
	v_lshlrev_b32_e32 v139, 16, v139
	v_pk_mul_f32 v[150:151], v[138:139], v[138:139]
	s_nop 0
	v_add_f32_e32 v151, v151, v154
	v_add_f32_e32 v150, v150, v151
	s_nop 1
	v_add_f32_dpp v150, v150, v150 quad_perm:[1,0,3,2] row_mask:0xf bank_mask:0xf bound_ctrl:1
	s_nop 1
	v_add_f32_dpp v150, v150, v150 quad_perm:[2,3,0,1] row_mask:0xf bank_mask:0xf bound_ctrl:1
	s_nop 1
	v_add_f32_dpp v150, v150, v150 row_half_mirror row_mask:0xf bank_mask:0xf bound_ctrl:1
	s_nop 1
	v_add_f32_dpp v150, v150, v150 row_mirror row_mask:0xf bank_mask:0xf bound_ctrl:1
	v_fmamk_f32 v150, v150, 0x3c000000, v177
	v_mul_f32_e32 v151, 0x4b800000, v150
	v_cmp_gt_f32_e32 vcc, s19, v150
	s_nop 1
	v_cndmask_b32_e32 v150, v150, v151, vcc
	v_rsq_f32_e32 v150, v150
	s_nop 0
	v_mul_f32_e32 v151, 0x45800000, v150
	v_cndmask_b32_e32 v150, v150, v151, vcc
	s_waitcnt vmcnt(0) lgkmcnt(0)
	v_mul_f32_e32 v140, v140, v150
	v_mul_f32_e32 v142, v142, v150
	v_mul_f32_e32 v140, v140, v152
	v_mul_f32_e32 v137, v142, v137
	v_mul_f32_e32 v142, v146, v150
	v_mul_f32_e32 v139, v142, v139
	v_mul_f32_e32 v142, v143, v150
	ds_bpermute_b32 v143, v176, v140
	v_mul_f32_e32 v141, v141, v150
	v_mul_f32_e32 v141, v141, v153
	v_mul_f32_e32 v136, v142, v136
	v_mul_f32_e32 v142, v147, v150
	v_mul_f32_e32 v138, v142, v138
	ds_bpermute_b32 v142, v176, v141
	s_waitcnt lgkmcnt(1)
	v_mul_f32_e32 v133, v133, v143
	v_cndmask_b32_e64 v133, v133, -v133, s[6:7]
	v_fmac_f32_e32 v133, v132, v140
	v_cndmask_b32_e64 v132, v140, v133, s[4:5]
	s_waitcnt lgkmcnt(0)
	v_mul_f32_e32 v133, v135, v142
	ds_bpermute_b32 v135, v176, v137
	v_cndmask_b32_e64 v133, v133, -v133, s[6:7]
	v_fmac_f32_e32 v133, v134, v141
	ds_bpermute_b32 v134, v176, v136
	v_mul_f32_e32 v144, v144, v150
	s_waitcnt lgkmcnt(1)
	v_mul_f32_e32 v129, v129, v135
	v_cndmask_b32_e64 v129, v129, -v129, s[6:7]
	v_mul_f32_e32 v144, v144, v149
	v_fmac_f32_e32 v129, v128, v137
	v_cndmask_b32_e64 v128, v137, v129, s[4:5]
	s_waitcnt lgkmcnt(0)
	v_mul_f32_e32 v129, v131, v134
	ds_bpermute_b32 v131, v176, v144
	v_mul_f32_e32 v145, v145, v150
	v_mul_f32_e32 v145, v145, v148
	v_cndmask_b32_e64 v129, v129, -v129, s[6:7]
	v_fmac_f32_e32 v129, v130, v136
	ds_bpermute_b32 v130, v176, v145
	s_waitcnt lgkmcnt(1)
	v_mul_f32_e32 v125, v125, v131
	v_cndmask_b32_e64 v125, v125, -v125, s[6:7]
	v_fmac_f32_e32 v125, v124, v144
	v_cndmask_b32_e64 v124, v144, v125, s[4:5]
	s_waitcnt lgkmcnt(0)
	v_mul_f32_e32 v125, v127, v130
	ds_bpermute_b32 v127, v176, v139
	v_cndmask_b32_e64 v125, v125, -v125, s[6:7]
	v_fmac_f32_e32 v125, v126, v145
	ds_bpermute_b32 v126, v176, v138
	v_cndmask_b32_e64 v133, v141, v133, s[4:5]
	s_waitcnt lgkmcnt(1)
	v_mul_f32_e32 v121, v121, v127
	v_cndmask_b32_e64 v121, v121, -v121, s[6:7]
	v_fmac_f32_e32 v121, v120, v139
	s_waitcnt lgkmcnt(0)
; __device__ __forceinline__ unsigned cvt_pk_bf16(float lo, float hi) { unsigned r; asm volatile("v_cvt_pk_bf16_f32 %0, %1, %2" : "=v"(r) : "v"(lo), "v"(hi)); return r; }
; __device__ __forceinline__ float shx(float v, int m, int lane) { return __int_as_float(__builtin_amdgcn_ds_bpermute((lane ^ m) << 2, __float_as_int(v))); }
; #define DPPF(v, ctrl) __int_as_float(__builtin_amdgcn_update_dpp(0, __float_as_int(v), (ctrl), 0xf, 0xf, false))
; __device__ __forceinline__ float row16_sum(float x) { x += DPPF(x, 0xB1); x += DPPF(x, 0x4E); x += DPPF(x, 0x141); x += DPPF(x, 0x140); return x; }
; template <bool NORM, int ROT> __device__ __forceinline__ void rope_chunk(bf16_t* p, const u32x4 w, const f32x4 (&tb)[4], const float* g, float sc, int lane) {
;     ...
;         float ss = 0.f;
; #pragma unroll
;         for (int q = 0; q < 8; ++q) ss += x[q] * x[q];
;         ss = row16_sum(ss);
;         const float rstd = rsqrtf(ss * (1.f / 128.f) + EPS);
;         const f32x4 g0 = *(const f32x4*)(g + j * 8), g1 = *(const f32x4*)(g + j * 8 + 4);
; #pragma unroll
;         for (int q = 0; q < 4; ++q) { x[q] *= rstd * g0[q]; x[4 + q] *= rstd * g1[q]; }
;     }
;     constexpr int HALFL = ROT / 16;
;     const bool rot = (ROT == 128) || (j < 8); const bool first = (j & HALFL) == 0;
;     float o[8];
; #pragma unroll
;     for (int q = 0; q < 8; ++q) {
;         const float other = (ROT == 128) ? DPPF(x[q], 0x128)   : shx(x[q], HALFL, lane);
;         const float cs = tb[q >> 1][(q & 1) * 2], sn = tb[q >> 1][(q & 1) * 2 + 1];
;         const float r = first ? (x[q] * cs - other * sn) : (x[q] * cs + other * sn);
;         o[q] = (rot ? r : x[q]) * sc;
;     }
;     u32x4 ow; ow.x = cvt_pk_bf16(o[0], o[1]); ow.y = cvt_pk_bf16(o[2], o[3]); ow.z = cvt_pk_bf16(o[4], o[5]); ow.w = cvt_pk_bf16(o[6], o[7]);
;     *(u32x4*)(p + lane * 8) = ow;
	v_mul_f32_e32 v120, v123, v126
	v_cndmask_b32_e64 v120, v120, -v120, s[6:7]
	v_fmac_f32_e32 v120, v122, v138
	v_cndmask_b32_e64 v123, v138, v120, s[4:5]
	v_cndmask_b32_e64 v129, v136, v129, s[4:5]
	v_cndmask_b32_e64 v125, v145, v125, s[4:5]
	v_cndmask_b32_e64 v127, v139, v121, s[4:5]
	v_cvt_pk_bf16_f32 v120, v132, v133
	v_cvt_pk_bf16_f32 v121, v128, v129
	v_cvt_pk_bf16_f32 v122, v124, v125
	v_cvt_pk_bf16_f32 v123, v127, v123
	flat_store_dwordx4 v[172:173], v[120:123]
	flat_load_dwordx4 v[120:123], v[160:161]
	s_nop 0
	flat_load_dwordx4 v[124:127], v[160:161] offset:16
	v_and_b32_e32 v133, 0xffff0000, v116
	v_lshlrev_b32_e32 v132, 16, v116
	v_mul_f32_e32 v130, v133, v133
	v_and_b32_e32 v116, 0xffff0000, v117
	v_lshlrev_b32_e32 v117, 16, v117
	v_fmac_f32_e32 v130, v132, v132
	v_pk_mul_f32 v[128:129], v[116:117], v[116:117]
	s_nop 0
	v_add_f32_e32 v129, v129, v130
	v_add_f32_e32 v134, v128, v129
	v_and_b32_e32 v128, 0xffff0000, v118
	v_lshlrev_b32_e32 v129, 16, v118
	v_pk_mul_f32 v[130:131], v[128:129], v[128:129]
	s_nop 0
	v_add_f32_e32 v118, v131, v134
	v_add_f32_e32 v134, v130, v118
	v_and_b32_e32 v118, 0xffff0000, v119
	v_lshlrev_b32_e32 v119, 16, v119
	v_pk_mul_f32 v[130:131], v[118:119], v[118:119]
	s_nop 0
	v_add_f32_e32 v131, v131, v134
	v_add_f32_e32 v130, v130, v131
	s_nop 1
	v_add_f32_dpp v130, v130, v130 quad_perm:[1,0,3,2] row_mask:0xf bank_mask:0xf bound_ctrl:1
	s_nop 1
	v_add_f32_dpp v130, v130, v130 quad_perm:[2,3,0,1] row_mask:0xf bank_mask:0xf bound_ctrl:1
	s_nop 1
	v_add_f32_dpp v130, v130, v130 row_half_mirror row_mask:0xf bank_mask:0xf bound_ctrl:1
	s_nop 1
	v_add_f32_dpp v130, v130, v130 row_mirror row_mask:0xf bank_mask:0xf bound_ctrl:1
	v_fmamk_f32 v130, v130, 0x3c000000, v177
	v_mul_f32_e32 v131, 0x4b800000, v130
	v_cmp_gt_f32_e32 vcc, s19, v130
	s_nop 1
	v_cndmask_b32_e32 v130, v130, v131, vcc
	v_rsq_f32_e32 v130, v130
	s_nop 0
	v_mul_f32_e32 v131, 0x45800000, v130
	v_cndmask_b32_e32 v130, v130, v131, vcc
	s_waitcnt vmcnt(0) lgkmcnt(0)
	v_mul_f32_e32 v120, v120, v130
	v_mul_f32_e32 v122, v122, v130
	v_mul_f32_e32 v120, v120, v132
	v_mul_f32_e32 v117, v122, v117
	v_mul_f32_e32 v122, v126, v130
	v_mul_f32_e32 v119, v122, v119
	v_mul_f32_e32 v122, v123, v130
	ds_bpermute_b32 v123, v176, v120
	v_mul_f32_e32 v121, v121, v130
	v_mul_f32_e32 v121, v121, v133
	v_mul_f32_e32 v116, v122, v116
	v_mul_f32_e32 v122, v127, v130
	v_mul_f32_e32 v118, v122, v118
	ds_bpermute_b32 v122, v176, v121
	s_waitcnt lgkmcnt(1)
	v_mul_f32_e32 v113, v113, v123
	v_cndmask_b32_e64 v113, v113, -v113, s[6:7]
	v_fmac_f32_e32 v113, v112, v120
	v_cndmask_b32_e64 v112, v120, v113, s[4:5]
	s_waitcnt lgkmcnt(0)
	v_mul_f32_e32 v113, v115, v122
	ds_bpermute_b32 v115, v176, v117
	v_cndmask_b32_e64 v113, v113, -v113, s[6:7]
	v_fmac_f32_e32 v113, v114, v121
	ds_bpermute_b32 v114, v176, v116
	v_mul_f32_e32 v124, v124, v130
	s_waitcnt lgkmcnt(1)
	v_mul_f32_e32 v109, v109, v115
	v_cndmask_b32_e64 v109, v109, -v109, s[6:7]
	v_mul_f32_e32 v124, v124, v129
	v_fmac_f32_e32 v109, v108, v117
	v_cndmask_b32_e64 v108, v117, v109, s[4:5]
	s_waitcnt lgkmcnt(0)
	v_mul_f32_e32 v109, v111, v114
	ds_bpermute_b32 v111, v176, v124
	v_mul_f32_e32 v125, v125, v130
	v_mul_f32_e32 v125, v125, v128
	v_cndmask_b32_e64 v109, v109, -v109, s[6:7]
	v_fmac_f32_e32 v109, v110, v116
	ds_bpermute_b32 v110, v176, v125
	s_waitcnt lgkmcnt(1)
	v_mul_f32_e32 v105, v105, v111
	v_cndmask_b32_e64 v105, v105, -v105, s[6:7]
	v_fmac_f32_e32 v105, v104, v124
	v_cndmask_b32_e64 v104, v124, v105, s[4:5]
	s_waitcnt lgkmcnt(0)
	v_mul_f32_e32 v105, v107, v110
	ds_bpermute_b32 v107, v176, v119
	v_cndmask_b32_e64 v105, v105, -v105, s[6:7]
	v_fmac_f32_e32 v105, v106, v125
	ds_bpermute_b32 v106, v176, v118
	v_cndmask_b32_e64 v113, v121, v113, s[4:5]
	s_waitcnt lgkmcnt(1)
	v_mul_f32_e32 v101, v101, v107
	v_cndmask_b32_e64 v101, v101, -v101, s[6:7]
	v_fmac_f32_e32 v101, v100, v119
	s_waitcnt lgkmcnt(0)
	v_mul_f32_e32 v100, v103, v106
	v_cndmask_b32_e64 v100, v100, -v100, s[6:7]
	v_fmac_f32_e32 v100, v102, v118
	v_cndmask_b32_e64 v103, v118, v100, s[4:5]
	v_cndmask_b32_e64 v109, v116, v109, s[4:5]
	v_cndmask_b32_e64 v105, v125, v105, s[4:5]
	v_cndmask_b32_e64 v107, v119, v101, s[4:5]
	v_cvt_pk_bf16_f32 v100, v112, v113
	v_cvt_pk_bf16_f32 v101, v108, v109
	v_cvt_pk_bf16_f32 v102, v104, v105
	v_cvt_pk_bf16_f32 v103, v107, v103
	flat_store_dwordx4 v[170:171], v[100:103]
	flat_load_dwordx4 v[100:103], v[160:161]
	s_nop 0
	flat_load_dwordx4 v[104:107], v[160:161] offset:16
	v_and_b32_e32 v113, 0xffff0000, v96
	v_lshlrev_b32_e32 v112, 16, v96
	v_mul_f32_e32 v110, v113, v113
	v_and_b32_e32 v96, 0xffff0000, v97
	v_lshlrev_b32_e32 v97, 16, v97
	v_fmac_f32_e32 v110, v112, v112
	v_pk_mul_f32 v[108:109], v[96:97], v[96:97]
	s_nop 0
	v_add_f32_e32 v109, v109, v110
	v_add_f32_e32 v114, v108, v109
	v_and_b32_e32 v108, 0xffff0000, v98
	v_lshlrev_b32_e32 v109, 16, v98
	v_pk_mul_f32 v[110:111], v[108:109], v[108:109]
	s_nop 0
	v_add_f32_e32 v98, v111, v114
	v_add_f32_e32 v114, v110, v98
	v_and_b32_e32 v98, 0xffff0000, v99
	v_lshlrev_b32_e32 v99, 16, v99
	v_pk_mul_f32 v[110:111], v[98:99], v[98:99]
	s_nop 0
	v_add_f32_e32 v111, v111, v114
	v_add_f32_e32 v110, v110, v111
	s_nop 1
	v_add_f32_dpp v110, v110, v110 quad_perm:[1,0,3,2] row_mask:0xf bank_mask:0xf bound_ctrl:1
	s_nop 1
	v_add_f32_dpp v110, v110, v110 quad_perm:[2,3,0,1] row_mask:0xf bank_mask:0xf bound_ctrl:1
	s_nop 1
	v_add_f32_dpp v110, v110, v110 row_half_mirror row_mask:0xf bank_mask:0xf bound_ctrl:1
	s_nop 1
	v_add_f32_dpp v110, v110, v110 row_mirror row_mask:0xf bank_mask:0xf bound_ctrl:1
	v_fmamk_f32 v110, v110, 0x3c000000, v177
	v_mul_f32_e32 v111, 0x4b800000, v110
	v_cmp_gt_f32_e32 vcc, s19, v110
	s_nop 1
	v_cndmask_b32_e32 v110, v110, v111, vcc
	v_rsq_f32_e32 v110, v110
	s_nop 0
	v_mul_f32_e32 v111, 0x45800000, v110
	v_cndmask_b32_e32 v110, v110, v111, vcc
	s_waitcnt vmcnt(0) lgkmcnt(0)
; __device__ __forceinline__ unsigned cvt_pk_bf16(float lo, float hi) { unsigned r; asm volatile("v_cvt_pk_bf16_f32 %0, %1, %2" : "=v"(r) : "v"(lo), "v"(hi)); return r; }
; __device__ __forceinline__ float shx(float v, int m, int lane) { return __int_as_float(__builtin_amdgcn_ds_bpermute((lane ^ m) << 2, __float_as_int(v))); }
; #define DPPF(v, ctrl) __int_as_float(__builtin_amdgcn_update_dpp(0, __float_as_int(v), (ctrl), 0xf, 0xf, false))
; __device__ __forceinline__ float row16_sum(float x) { x += DPPF(x, 0xB1); x += DPPF(x, 0x4E); x += DPPF(x, 0x141); x += DPPF(x, 0x140); return x; }
; template <bool NORM, int ROT> __device__ __forceinline__ void rope_chunk(bf16_t* p, const u32x4 w, const f32x4 (&tb)[4], const float* g, float sc, int lane) {
;     ...
;         float ss = 0.f;
; #pragma unroll
;         for (int q = 0; q < 8; ++q) ss += x[q] * x[q];
;         ss = row16_sum(ss);
;         const float rstd = rsqrtf(ss * (1.f / 128.f) + EPS);
;         const f32x4 g0 = *(const f32x4*)(g + j * 8), g1 = *(const f32x4*)(g + j * 8 + 4);
; #pragma unroll
;         for (int q = 0; q < 4; ++q) { x[q] *= rstd * g0[q]; x[4 + q] *= rstd * g1[q]; }
;     }
;     constexpr int HALFL = ROT / 16;
;     const bool rot = (ROT == 128) || (j < 8); const bool first = (j & HALFL) == 0;
;     float o[8];
; #pragma unroll
;     for (int q = 0; q < 8; ++q) {
;         const float other = (ROT == 128) ? DPPF(x[q], 0x128)   : shx(x[q], HALFL, lane);
;         const float cs = tb[q >> 1][(q & 1) * 2], sn = tb[q >> 1][(q & 1) * 2 + 1];
;         const float r = first ? (x[q] * cs - other * sn) : (x[q] * cs + other * sn);
;         o[q] = (rot ? r : x[q]) * sc;
;     }
;     u32x4 ow; ow.x = cvt_pk_bf16(o[0], o[1]); ow.y = cvt_pk_bf16(o[2], o[3]); ow.z = cvt_pk_bf16(o[4], o[5]); ow.w = cvt_pk_bf16(o[6], o[7]);
;     *(u32x4*)(p + lane * 8) = ow;
	v_mul_f32_e32 v100, v100, v110
	v_mul_f32_e32 v102, v102, v110
	v_mul_f32_e32 v100, v100, v112
	v_mul_f32_e32 v97, v102, v97
	v_mul_f32_e32 v102, v106, v110
	v_mul_f32_e32 v99, v102, v99
	v_mul_f32_e32 v102, v103, v110
	ds_bpermute_b32 v103, v176, v100
	v_mul_f32_e32 v101, v101, v110
	v_mul_f32_e32 v101, v101, v113
	v_mul_f32_e32 v96, v102, v96
	v_mul_f32_e32 v102, v107, v110
	v_mul_f32_e32 v98, v102, v98
	ds_bpermute_b32 v102, v176, v101
	s_waitcnt lgkmcnt(1)
	v_mul_f32_e32 v93, v93, v103
	v_cndmask_b32_e64 v93, v93, -v93, s[6:7]
	v_fmac_f32_e32 v93, v92, v100
	v_cndmask_b32_e64 v92, v100, v93, s[4:5]
	s_waitcnt lgkmcnt(0)
	v_mul_f32_e32 v93, v95, v102
	ds_bpermute_b32 v95, v176, v97
	v_cndmask_b32_e64 v93, v93, -v93, s[6:7]
	v_fmac_f32_e32 v93, v94, v101
	ds_bpermute_b32 v94, v176, v96
	v_mul_f32_e32 v104, v104, v110
	s_waitcnt lgkmcnt(1)
	v_mul_f32_e32 v89, v89, v95
	v_cndmask_b32_e64 v89, v89, -v89, s[6:7]
	v_mul_f32_e32 v104, v104, v109
	v_fmac_f32_e32 v89, v88, v97
	v_cndmask_b32_e64 v88, v97, v89, s[4:5]
	s_waitcnt lgkmcnt(0)
	v_mul_f32_e32 v89, v91, v94
	ds_bpermute_b32 v91, v176, v104
	v_mul_f32_e32 v105, v105, v110
	v_mul_f32_e32 v105, v105, v108
	v_cndmask_b32_e64 v89, v89, -v89, s[6:7]
	v_fmac_f32_e32 v89, v90, v96
	ds_bpermute_b32 v90, v176, v105
	s_waitcnt lgkmcnt(1)
	v_mul_f32_e32 v85, v85, v91
	v_cndmask_b32_e64 v85, v85, -v85, s[6:7]
	v_fmac_f32_e32 v85, v84, v104
	v_cndmask_b32_e64 v84, v104, v85, s[4:5]
	s_waitcnt lgkmcnt(0)
	v_mul_f32_e32 v85, v87, v90
	ds_bpermute_b32 v87, v176, v99
	v_cndmask_b32_e64 v85, v85, -v85, s[6:7]
	v_fmac_f32_e32 v85, v86, v105
	ds_bpermute_b32 v86, v176, v98
	v_cndmask_b32_e64 v93, v101, v93, s[4:5]
	s_waitcnt lgkmcnt(1)
	v_mul_f32_e32 v81, v81, v87
	v_cndmask_b32_e64 v81, v81, -v81, s[6:7]
	v_fmac_f32_e32 v81, v80, v99
	s_waitcnt lgkmcnt(0)
	v_mul_f32_e32 v80, v83, v86
	v_cndmask_b32_e64 v80, v80, -v80, s[6:7]
	v_fmac_f32_e32 v80, v82, v98
	v_cndmask_b32_e64 v83, v98, v80, s[4:5]
	v_cndmask_b32_e64 v89, v96, v89, s[4:5]
	v_cndmask_b32_e64 v85, v105, v85, s[4:5]
	v_cndmask_b32_e64 v87, v99, v81, s[4:5]
	v_cvt_pk_bf16_f32 v80, v92, v93
	v_cvt_pk_bf16_f32 v81, v88, v89
	v_cvt_pk_bf16_f32 v82, v84, v85
	v_cvt_pk_bf16_f32 v83, v87, v83
	flat_store_dwordx4 v[168:169], v[80:83]
	flat_load_dwordx4 v[80:83], v[160:161]
	s_nop 0
	flat_load_dwordx4 v[84:87], v[160:161] offset:16
	v_and_b32_e32 v93, 0xffff0000, v60
	v_lshlrev_b32_e32 v92, 16, v60
	v_mul_f32_e32 v90, v93, v93
	v_and_b32_e32 v60, 0xffff0000, v61
	v_lshlrev_b32_e32 v61, 16, v61
	v_fmac_f32_e32 v90, v92, v92
	v_pk_mul_f32 v[88:89], v[60:61], v[60:61]
	s_nop 0
	v_add_f32_e32 v89, v89, v90
	v_add_f32_e32 v94, v88, v89
	v_and_b32_e32 v88, 0xffff0000, v62
	v_lshlrev_b32_e32 v89, 16, v62
	v_pk_mul_f32 v[90:91], v[88:89], v[88:89]
	s_nop 0
	v_add_f32_e32 v62, v91, v94
	v_add_f32_e32 v94, v90, v62
	v_and_b32_e32 v62, 0xffff0000, v63
	v_lshlrev_b32_e32 v63, 16, v63
	v_pk_mul_f32 v[90:91], v[62:63], v[62:63]
	s_nop 0
	v_add_f32_e32 v91, v91, v94
	v_add_f32_e32 v90, v90, v91
	s_nop 1
	v_add_f32_dpp v90, v90, v90 quad_perm:[1,0,3,2] row_mask:0xf bank_mask:0xf bound_ctrl:1
	s_nop 1
	v_add_f32_dpp v90, v90, v90 quad_perm:[2,3,0,1] row_mask:0xf bank_mask:0xf bound_ctrl:1
	s_nop 1
	v_add_f32_dpp v90, v90, v90 row_half_mirror row_mask:0xf bank_mask:0xf bound_ctrl:1
	s_nop 1
	v_add_f32_dpp v90, v90, v90 row_mirror row_mask:0xf bank_mask:0xf bound_ctrl:1
	v_fmamk_f32 v90, v90, 0x3c000000, v177
	v_mul_f32_e32 v91, 0x4b800000, v90
	v_cmp_gt_f32_e32 vcc, s19, v90
	s_nop 1
	v_cndmask_b32_e32 v90, v90, v91, vcc
	v_rsq_f32_e32 v90, v90
	s_nop 0
	v_mul_f32_e32 v91, 0x45800000, v90
	v_cndmask_b32_e32 v90, v90, v91, vcc
	s_waitcnt vmcnt(0) lgkmcnt(0)
	v_mul_f32_e32 v80, v80, v90
	v_mul_f32_e32 v82, v82, v90
	v_mul_f32_e32 v80, v80, v92
	v_mul_f32_e32 v61, v82, v61
	v_mul_f32_e32 v82, v86, v90
	v_mul_f32_e32 v63, v82, v63
	v_mul_f32_e32 v82, v83, v90
	ds_bpermute_b32 v83, v176, v80
	v_mul_f32_e32 v81, v81, v90
	v_mul_f32_e32 v81, v81, v93
	v_mul_f32_e32 v60, v82, v60
	v_mul_f32_e32 v82, v87, v90
	v_mul_f32_e32 v62, v82, v62
	ds_bpermute_b32 v82, v176, v81
	s_waitcnt lgkmcnt(1)
	v_mul_f32_e32 v77, v77, v83
	v_cndmask_b32_e64 v77, v77, -v77, s[6:7]
	v_fmac_f32_e32 v77, v76, v80
	v_cndmask_b32_e64 v76, v80, v77, s[4:5]
	s_waitcnt lgkmcnt(0)
	v_mul_f32_e32 v77, v79, v82
	ds_bpermute_b32 v79, v176, v61
	v_cndmask_b32_e64 v77, v77, -v77, s[6:7]
	v_fmac_f32_e32 v77, v78, v81
	ds_bpermute_b32 v78, v176, v60
	v_mul_f32_e32 v84, v84, v90
	s_waitcnt lgkmcnt(1)
	v_mul_f32_e32 v73, v73, v79
	v_cndmask_b32_e64 v73, v73, -v73, s[6:7]
	v_fmac_f32_e32 v73, v72, v61
	s_waitcnt lgkmcnt(0)
	v_mul_f32_e32 v72, v75, v78
	v_mul_f32_e32 v84, v84, v89
	v_mul_f32_e32 v85, v85, v90
	v_cndmask_b32_e64 v72, v72, -v72, s[6:7]
	v_mul_f32_e32 v85, v85, v88
	v_cndmask_b32_e64 v61, v61, v73, s[4:5]
	ds_bpermute_b32 v73, v176, v84
	v_fmac_f32_e32 v72, v74, v60
	v_cndmask_b32_e64 v72, v60, v72, s[4:5]
	ds_bpermute_b32 v60, v176, v85
	v_cndmask_b32_e64 v77, v81, v77, s[4:5]
	s_waitcnt lgkmcnt(1)
	v_mul_f32_e32 v69, v69, v73
	v_cndmask_b32_e64 v69, v69, -v69, s[6:7]
	v_fmac_f32_e32 v69, v68, v84
	s_waitcnt lgkmcnt(0)
	v_mul_f32_e32 v60, v71, v60
	v_cndmask_b32_e64 v60, v60, -v60, s[6:7]
	v_cndmask_b32_e64 v68, v84, v69, s[4:5]
	ds_bpermute_b32 v69, v176, v63
	v_fmac_f32_e32 v60, v70, v85
	v_cndmask_b32_e64 v70, v85, v60, s[4:5]
	ds_bpermute_b32 v60, v176, v62
	v_and_b32_e32 v73, 0xffff0000, v56
	s_waitcnt lgkmcnt(1)
	v_mul_f32_e32 v65, v65, v69
	v_cndmask_b32_e64 v65, v65, -v65, s[6:7]
	v_fmac_f32_e32 v65, v64, v63
	s_waitcnt lgkmcnt(0)
; __device__ __forceinline__ unsigned cvt_pk_bf16(float lo, float hi) { unsigned r; asm volatile("v_cvt_pk_bf16_f32 %0, %1, %2" : "=v"(r) : "v"(lo), "v"(hi)); return r; }
; __device__ __forceinline__ float shx(float v, int m, int lane) { return __int_as_float(__builtin_amdgcn_ds_bpermute((lane ^ m) << 2, __float_as_int(v))); }
; #define DPPF(v, ctrl) __int_as_float(__builtin_amdgcn_update_dpp(0, __float_as_int(v), (ctrl), 0xf, 0xf, false))
; __device__ __forceinline__ float row16_sum(float x) { x += DPPF(x, 0xB1); x += DPPF(x, 0x4E); x += DPPF(x, 0x141); x += DPPF(x, 0x140); return x; }
; template <bool NORM, int ROT> __device__ __forceinline__ void rope_chunk(bf16_t* p, const u32x4 w, const f32x4 (&tb)[4], const float* g, float sc, int lane) {
;     ...
;         float ss = 0.f;
; #pragma unroll
;         for (int q = 0; q < 8; ++q) ss += x[q] * x[q];
;         ss = row16_sum(ss);
;         const float rstd = rsqrtf(ss * (1.f / 128.f) + EPS);
;         const f32x4 g0 = *(const f32x4*)(g + j * 8), g1 = *(const f32x4*)(g + j * 8 + 4);
; #pragma unroll
;         for (int q = 0; q < 4; ++q) { x[q] *= rstd * g0[q]; x[4 + q] *= rstd * g1[q]; }
;     }
;     constexpr int HALFL = ROT / 16;
;     const bool rot = (ROT == 128) || (j < 8); const bool first = (j & HALFL) == 0;
;     float o[8];
; #pragma unroll
;     for (int q = 0; q < 8; ++q) {
;         const float other = (ROT == 128) ? DPPF(x[q], 0x128)   : shx(x[q], HALFL, lane);
;         const float cs = tb[q >> 1][(q & 1) * 2], sn = tb[q >> 1][(q & 1) * 2 + 1];
;         const float r = first ? (x[q] * cs - other * sn) : (x[q] * cs + other * sn);
;         o[q] = (rot ? r : x[q]) * sc;
;     }
;     u32x4 ow; ow.x = cvt_pk_bf16(o[0], o[1]); ow.y = cvt_pk_bf16(o[2], o[3]); ow.z = cvt_pk_bf16(o[4], o[5]); ow.w = cvt_pk_bf16(o[6], o[7]);
;     *(u32x4*)(p + lane * 8) = ow;
	v_mul_f32_e32 v60, v67, v60
	v_cndmask_b32_e64 v60, v60, -v60, s[6:7]
	v_cndmask_b32_e64 v63, v63, v65, s[4:5]
	v_fmac_f32_e32 v60, v66, v62
	v_cndmask_b32_e64 v64, v62, v60, s[4:5]
	v_cvt_pk_bf16_f32 v60, v76, v77
	v_cvt_pk_bf16_f32 v61, v61, v72
	v_cvt_pk_bf16_f32 v62, v68, v70
	v_cvt_pk_bf16_f32 v63, v63, v64
	flat_store_dwordx4 v[166:167], v[60:63]
	flat_load_dwordx4 v[60:63], v[160:161]
	s_nop 0
	flat_load_dwordx4 v[64:67], v[160:161] offset:16
	v_lshlrev_b32_e32 v72, 16, v56
	v_mul_f32_e32 v70, v73, v73
	v_and_b32_e32 v56, 0xffff0000, v57
	v_lshlrev_b32_e32 v57, 16, v57
	v_fmac_f32_e32 v70, v72, v72
	v_pk_mul_f32 v[68:69], v[56:57], v[56:57]
	s_nop 0
	v_add_f32_e32 v69, v69, v70
	v_add_f32_e32 v74, v68, v69
	v_and_b32_e32 v68, 0xffff0000, v58
	v_lshlrev_b32_e32 v69, 16, v58
	v_pk_mul_f32 v[70:71], v[68:69], v[68:69]
	s_nop 0
	v_add_f32_e32 v58, v71, v74
	v_add_f32_e32 v74, v70, v58
	v_and_b32_e32 v58, 0xffff0000, v59
	v_lshlrev_b32_e32 v59, 16, v59
	v_pk_mul_f32 v[70:71], v[58:59], v[58:59]
	s_nop 0
	v_add_f32_e32 v71, v71, v74
	v_add_f32_e32 v70, v70, v71
	s_nop 1
	v_add_f32_dpp v70, v70, v70 quad_perm:[1,0,3,2] row_mask:0xf bank_mask:0xf bound_ctrl:1
	s_nop 1
	v_add_f32_dpp v70, v70, v70 quad_perm:[2,3,0,1] row_mask:0xf bank_mask:0xf bound_ctrl:1
	s_nop 1
	v_add_f32_dpp v70, v70, v70 row_half_mirror row_mask:0xf bank_mask:0xf bound_ctrl:1
	s_nop 1
	v_add_f32_dpp v70, v70, v70 row_mirror row_mask:0xf bank_mask:0xf bound_ctrl:1
	v_fmamk_f32 v70, v70, 0x3c000000, v177
	v_mul_f32_e32 v71, 0x4b800000, v70
	v_cmp_gt_f32_e32 vcc, s19, v70
	s_nop 1
	v_cndmask_b32_e32 v70, v70, v71, vcc
	v_rsq_f32_e32 v70, v70
	s_nop 0
	v_mul_f32_e32 v71, 0x45800000, v70
	v_cndmask_b32_e32 v70, v70, v71, vcc
	s_waitcnt vmcnt(0) lgkmcnt(0)
	v_mul_f32_e32 v60, v60, v70
	v_mul_f32_e32 v62, v62, v70
	v_mul_f32_e32 v60, v60, v72
	v_mul_f32_e32 v57, v62, v57
	v_mul_f32_e32 v62, v66, v70
	v_mul_f32_e32 v59, v62, v59
	v_mul_f32_e32 v62, v63, v70
	ds_bpermute_b32 v63, v176, v60
	v_mul_f32_e32 v61, v61, v70
	v_mul_f32_e32 v61, v61, v73
	v_mul_f32_e32 v56, v62, v56
	v_mul_f32_e32 v62, v67, v70
	v_mul_f32_e32 v58, v62, v58
	ds_bpermute_b32 v62, v176, v61
	s_waitcnt lgkmcnt(1)
	v_mul_f32_e32 v53, v53, v63
	v_cndmask_b32_e64 v53, v53, -v53, s[6:7]
	v_fmac_f32_e32 v53, v52, v60
	v_cndmask_b32_e64 v52, v60, v53, s[4:5]
	s_waitcnt lgkmcnt(0)
	v_mul_f32_e32 v53, v55, v62
	ds_bpermute_b32 v55, v176, v57
	v_cndmask_b32_e64 v53, v53, -v53, s[6:7]
	v_fmac_f32_e32 v53, v54, v61
	ds_bpermute_b32 v54, v176, v56
	v_mul_f32_e32 v64, v64, v70
	s_waitcnt lgkmcnt(1)
	v_mul_f32_e32 v49, v49, v55
	v_cndmask_b32_e64 v49, v49, -v49, s[6:7]
	v_mul_f32_e32 v64, v64, v69
	v_fmac_f32_e32 v49, v48, v57
	v_cndmask_b32_e64 v48, v57, v49, s[4:5]
	s_waitcnt lgkmcnt(0)
	v_mul_f32_e32 v49, v51, v54
	ds_bpermute_b32 v51, v176, v64
	v_mul_f32_e32 v65, v65, v70
	v_mul_f32_e32 v65, v65, v68
	v_cndmask_b32_e64 v49, v49, -v49, s[6:7]
	v_fmac_f32_e32 v49, v50, v56
	ds_bpermute_b32 v50, v176, v65
	s_waitcnt lgkmcnt(1)
	v_mul_f32_e32 v45, v45, v51
	v_cndmask_b32_e64 v45, v45, -v45, s[6:7]
	v_fmac_f32_e32 v45, v44, v64
	v_cndmask_b32_e64 v44, v64, v45, s[4:5]
	s_waitcnt lgkmcnt(0)
	v_mul_f32_e32 v45, v47, v50
	ds_bpermute_b32 v47, v176, v59
	v_cndmask_b32_e64 v45, v45, -v45, s[6:7]
	v_fmac_f32_e32 v45, v46, v65
	ds_bpermute_b32 v46, v176, v58
	v_cndmask_b32_e64 v53, v61, v53, s[4:5]
	s_waitcnt lgkmcnt(1)
	v_mul_f32_e32 v41, v41, v47
	v_cndmask_b32_e64 v41, v41, -v41, s[6:7]
	v_fmac_f32_e32 v41, v40, v59
	s_waitcnt lgkmcnt(0)
	v_mul_f32_e32 v40, v43, v46
	v_cndmask_b32_e64 v40, v40, -v40, s[6:7]
	v_fmac_f32_e32 v40, v42, v58
	v_cndmask_b32_e64 v43, v58, v40, s[4:5]
	v_cndmask_b32_e64 v49, v56, v49, s[4:5]
	v_cndmask_b32_e64 v45, v65, v45, s[4:5]
	v_cndmask_b32_e64 v47, v59, v41, s[4:5]
	v_cvt_pk_bf16_f32 v40, v52, v53
	v_cvt_pk_bf16_f32 v41, v48, v49
	v_cvt_pk_bf16_f32 v42, v44, v45
	v_cvt_pk_bf16_f32 v43, v47, v43
	flat_store_dwordx4 v[164:165], v[40:43]
	flat_load_dwordx4 v[40:43], v[160:161]
	s_nop 0
	flat_load_dwordx4 v[44:47], v[160:161] offset:16
	v_and_b32_e32 v53, 0xffff0000, v36
	v_lshlrev_b32_e32 v52, 16, v36
	v_mul_f32_e32 v50, v53, v53
	v_and_b32_e32 v36, 0xffff0000, v37
	v_lshlrev_b32_e32 v37, 16, v37
	v_fmac_f32_e32 v50, v52, v52
	v_pk_mul_f32 v[48:49], v[36:37], v[36:37]
	s_nop 0
	v_add_f32_e32 v49, v49, v50
	v_add_f32_e32 v54, v48, v49
	v_and_b32_e32 v48, 0xffff0000, v38
	v_lshlrev_b32_e32 v49, 16, v38
	v_pk_mul_f32 v[50:51], v[48:49], v[48:49]
	s_nop 0
	v_add_f32_e32 v38, v51, v54
	v_add_f32_e32 v54, v50, v38
	v_and_b32_e32 v38, 0xffff0000, v39
	v_lshlrev_b32_e32 v39, 16, v39
	v_pk_mul_f32 v[50:51], v[38:39], v[38:39]
	s_nop 0
	v_add_f32_e32 v51, v51, v54
	v_add_f32_e32 v50, v50, v51
	s_nop 1
	v_add_f32_dpp v50, v50, v50 quad_perm:[1,0,3,2] row_mask:0xf bank_mask:0xf bound_ctrl:1
	s_nop 1
	v_add_f32_dpp v50, v50, v50 quad_perm:[2,3,0,1] row_mask:0xf bank_mask:0xf bound_ctrl:1
	s_nop 1
	v_add_f32_dpp v50, v50, v50 row_half_mirror row_mask:0xf bank_mask:0xf bound_ctrl:1
	s_nop 1
	v_add_f32_dpp v50, v50, v50 row_mirror row_mask:0xf bank_mask:0xf bound_ctrl:1
	v_fmamk_f32 v50, v50, 0x3c000000, v177
	v_mul_f32_e32 v51, 0x4b800000, v50
	v_cmp_gt_f32_e32 vcc, s19, v50
	s_nop 1
	v_cndmask_b32_e32 v50, v50, v51, vcc
	v_rsq_f32_e32 v50, v50
	s_nop 0
	v_mul_f32_e32 v51, 0x45800000, v50
	v_cndmask_b32_e32 v50, v50, v51, vcc
	s_waitcnt vmcnt(0) lgkmcnt(0)
	v_mul_f32_e32 v40, v40, v50
	v_mul_f32_e32 v42, v42, v50
	v_mul_f32_e32 v40, v40, v52
	v_mul_f32_e32 v37, v42, v37
	v_mul_f32_e32 v42, v46, v50
	v_mul_f32_e32 v39, v42, v39
	v_mul_f32_e32 v42, v43, v50
	ds_bpermute_b32 v43, v176, v40
	v_mul_f32_e32 v41, v41, v50
	v_mul_f32_e32 v41, v41, v53
	v_mul_f32_e32 v36, v42, v36
	v_mul_f32_e32 v42, v47, v50
	v_mul_f32_e32 v38, v42, v38
	ds_bpermute_b32 v42, v176, v41
	s_waitcnt lgkmcnt(1)
; __device__ __forceinline__ unsigned cvt_pk_bf16(float lo, float hi) { unsigned r; asm volatile("v_cvt_pk_bf16_f32 %0, %1, %2" : "=v"(r) : "v"(lo), "v"(hi)); return r; }
; __device__ __forceinline__ float shx(float v, int m, int lane) { return __int_as_float(__builtin_amdgcn_ds_bpermute((lane ^ m) << 2, __float_as_int(v))); }
; #define DPPF(v, ctrl) __int_as_float(__builtin_amdgcn_update_dpp(0, __float_as_int(v), (ctrl), 0xf, 0xf, false))
; __device__ __forceinline__ float row16_sum(float x) { x += DPPF(x, 0xB1); x += DPPF(x, 0x4E); x += DPPF(x, 0x141); x += DPPF(x, 0x140); return x; }
; template <bool NORM, int ROT> __device__ __forceinline__ void rope_chunk(bf16_t* p, const u32x4 w, const f32x4 (&tb)[4], const float* g, float sc, int lane) {
;     ...
;         float ss = 0.f;
; #pragma unroll
;         for (int q = 0; q < 8; ++q) ss += x[q] * x[q];
;         ss = row16_sum(ss);
;         const float rstd = rsqrtf(ss * (1.f / 128.f) + EPS);
;         const f32x4 g0 = *(const f32x4*)(g + j * 8), g1 = *(const f32x4*)(g + j * 8 + 4);
; #pragma unroll
;         for (int q = 0; q < 4; ++q) { x[q] *= rstd * g0[q]; x[4 + q] *= rstd * g1[q]; }
;     }
;     constexpr int HALFL = ROT / 16;
;     const bool rot = (ROT == 128) || (j < 8); const bool first = (j & HALFL) == 0;
;     float o[8];
; #pragma unroll
;     for (int q = 0; q < 8; ++q) {
;         const float other = (ROT == 128) ? DPPF(x[q], 0x128)   : shx(x[q], HALFL, lane);
;         const float cs = tb[q >> 1][(q & 1) * 2], sn = tb[q >> 1][(q & 1) * 2 + 1];
;         const float r = first ? (x[q] * cs - other * sn) : (x[q] * cs + other * sn);
;         o[q] = (rot ? r : x[q]) * sc;
;     }
;     u32x4 ow; ow.x = cvt_pk_bf16(o[0], o[1]); ow.y = cvt_pk_bf16(o[2], o[3]); ow.z = cvt_pk_bf16(o[4], o[5]); ow.w = cvt_pk_bf16(o[6], o[7]);
;     *(u32x4*)(p + lane * 8) = ow;
; template <bool NORM, int ROT, bool PERTOK> __device__ __forceinline__ void rope_pass(bf16_t* base, int nchunks, const float* g, const float* tab, float sc, int gw, int NGW, int lane) {
;     ...
;     for (int it0 = gw * NB; it0 < nchunks; it0 += NGW * NB) {
	v_mul_f32_e32 v33, v33, v43
	v_cndmask_b32_e64 v33, v33, -v33, s[6:7]
	v_fmac_f32_e32 v33, v32, v40
	v_cndmask_b32_e64 v32, v40, v33, s[4:5]
	s_waitcnt lgkmcnt(0)
	v_mul_f32_e32 v33, v35, v42
	ds_bpermute_b32 v35, v176, v37
	v_cndmask_b32_e64 v33, v33, -v33, s[6:7]
	v_fmac_f32_e32 v33, v34, v41
	ds_bpermute_b32 v34, v176, v36
	v_mul_f32_e32 v44, v44, v50
	s_waitcnt lgkmcnt(1)
	v_mul_f32_e32 v29, v29, v35
	v_cndmask_b32_e64 v29, v29, -v29, s[6:7]
	v_mul_f32_e32 v44, v44, v49
	v_fmac_f32_e32 v29, v28, v37
	v_cndmask_b32_e64 v28, v37, v29, s[4:5]
	s_waitcnt lgkmcnt(0)
	v_mul_f32_e32 v29, v31, v34
	ds_bpermute_b32 v31, v176, v44
	v_mul_f32_e32 v45, v45, v50
	v_mul_f32_e32 v45, v45, v48
	v_cndmask_b32_e64 v29, v29, -v29, s[6:7]
	v_fmac_f32_e32 v29, v30, v36
	ds_bpermute_b32 v30, v176, v45
	s_waitcnt lgkmcnt(1)
	v_mul_f32_e32 v25, v25, v31
	v_cndmask_b32_e64 v25, v25, -v25, s[6:7]
	v_fmac_f32_e32 v25, v24, v44
	v_cndmask_b32_e64 v24, v44, v25, s[4:5]
	s_waitcnt lgkmcnt(0)
	v_mul_f32_e32 v25, v27, v30
	ds_bpermute_b32 v27, v176, v39
	v_cndmask_b32_e64 v25, v25, -v25, s[6:7]
	v_fmac_f32_e32 v25, v26, v45
	ds_bpermute_b32 v26, v176, v38
	v_cndmask_b32_e64 v33, v41, v33, s[4:5]
	s_waitcnt lgkmcnt(1)
	v_mul_f32_e32 v21, v21, v27
	v_cndmask_b32_e64 v21, v21, -v21, s[6:7]
	v_fmac_f32_e32 v21, v20, v39
	s_waitcnt lgkmcnt(0)
	v_mul_f32_e32 v20, v23, v26
	v_cndmask_b32_e64 v20, v20, -v20, s[6:7]
	v_fmac_f32_e32 v20, v22, v38
	v_cndmask_b32_e64 v23, v38, v20, s[4:5]
	v_cndmask_b32_e64 v29, v36, v29, s[4:5]
	v_cndmask_b32_e64 v25, v45, v25, s[4:5]
	v_cndmask_b32_e64 v27, v39, v21, s[4:5]
	v_cvt_pk_bf16_f32 v20, v32, v33
	v_cvt_pk_bf16_f32 v21, v28, v29
	v_cvt_pk_bf16_f32 v22, v24, v25
	v_cvt_pk_bf16_f32 v23, v27, v23
	flat_store_dwordx4 v[162:163], v[20:23]
	flat_load_dwordx4 v[20:23], v[160:161]
	s_nop 0
	flat_load_dwordx4 v[24:27], v[160:161] offset:16
	v_and_b32_e32 v33, 0xffff0000, v16
	v_lshlrev_b32_e32 v32, 16, v16
	v_mul_f32_e32 v30, v33, v33
	v_and_b32_e32 v16, 0xffff0000, v17
	v_lshlrev_b32_e32 v17, 16, v17
	v_fmac_f32_e32 v30, v32, v32
	v_pk_mul_f32 v[28:29], v[16:17], v[16:17]
	s_nop 0
	v_add_f32_e32 v29, v29, v30
	v_add_f32_e32 v34, v28, v29
	v_and_b32_e32 v28, 0xffff0000, v18
	v_lshlrev_b32_e32 v29, 16, v18
	v_pk_mul_f32 v[30:31], v[28:29], v[28:29]
	s_nop 0
	v_add_f32_e32 v18, v31, v34
	v_add_f32_e32 v34, v30, v18
	v_and_b32_e32 v18, 0xffff0000, v19
	v_lshlrev_b32_e32 v19, 16, v19
	v_pk_mul_f32 v[30:31], v[18:19], v[18:19]
	s_nop 0
	v_add_f32_e32 v31, v31, v34
	v_add_f32_e32 v30, v30, v31
	s_nop 1
	v_add_f32_dpp v30, v30, v30 quad_perm:[1,0,3,2] row_mask:0xf bank_mask:0xf bound_ctrl:1
	s_nop 1
	v_add_f32_dpp v30, v30, v30 quad_perm:[2,3,0,1] row_mask:0xf bank_mask:0xf bound_ctrl:1
	s_nop 1
	v_add_f32_dpp v30, v30, v30 row_half_mirror row_mask:0xf bank_mask:0xf bound_ctrl:1
	s_nop 1
	v_add_f32_dpp v30, v30, v30 row_mirror row_mask:0xf bank_mask:0xf bound_ctrl:1
	v_fmamk_f32 v30, v30, 0x3c000000, v177
	v_mul_f32_e32 v31, 0x4b800000, v30
	v_cmp_gt_f32_e32 vcc, s19, v30
	s_nop 1
	v_cndmask_b32_e32 v30, v30, v31, vcc
	v_rsq_f32_e32 v30, v30
	s_nop 0
	v_mul_f32_e32 v31, 0x45800000, v30
	v_cndmask_b32_e32 v30, v30, v31, vcc
	s_waitcnt vmcnt(0) lgkmcnt(0)
	v_mul_f32_e32 v20, v20, v30
	v_mul_f32_e32 v22, v22, v30
	v_mul_f32_e32 v20, v20, v32
	v_mul_f32_e32 v17, v22, v17
	v_mul_f32_e32 v22, v26, v30
	v_mul_f32_e32 v19, v22, v19
	v_mul_f32_e32 v22, v23, v30
	ds_bpermute_b32 v23, v176, v20
	v_mul_f32_e32 v21, v21, v30
	v_mul_f32_e32 v21, v21, v33
	v_mul_f32_e32 v16, v22, v16
	v_mul_f32_e32 v22, v27, v30
	v_mul_f32_e32 v18, v22, v18
	ds_bpermute_b32 v22, v176, v21
	s_waitcnt lgkmcnt(1)
	v_mul_f32_e32 v13, v13, v23
	v_cndmask_b32_e64 v13, v13, -v13, s[6:7]
	v_fmac_f32_e32 v13, v12, v20
	v_cndmask_b32_e64 v12, v20, v13, s[4:5]
	s_waitcnt lgkmcnt(0)
	v_mul_f32_e32 v13, v15, v22
	ds_bpermute_b32 v15, v176, v17
	v_cndmask_b32_e64 v13, v13, -v13, s[6:7]
	v_fmac_f32_e32 v13, v14, v21
	ds_bpermute_b32 v14, v176, v16
	v_mul_f32_e32 v24, v24, v30
	s_waitcnt lgkmcnt(1)
	v_mul_f32_e32 v9, v9, v15
	v_cndmask_b32_e64 v9, v9, -v9, s[6:7]
	v_mul_f32_e32 v24, v24, v29
	v_fmac_f32_e32 v9, v8, v17
	v_cndmask_b32_e64 v8, v17, v9, s[4:5]
	s_waitcnt lgkmcnt(0)
	v_mul_f32_e32 v9, v11, v14
	ds_bpermute_b32 v11, v176, v24
	v_mul_f32_e32 v25, v25, v30
	v_mul_f32_e32 v25, v25, v28
	v_cndmask_b32_e64 v9, v9, -v9, s[6:7]
	v_fmac_f32_e32 v9, v10, v16
	ds_bpermute_b32 v10, v176, v25
	s_waitcnt lgkmcnt(1)
	v_mul_f32_e32 v5, v5, v11
	v_cndmask_b32_e64 v5, v5, -v5, s[6:7]
	v_fmac_f32_e32 v5, v4, v24
	v_cndmask_b32_e64 v4, v24, v5, s[4:5]
	s_waitcnt lgkmcnt(0)
	v_mul_f32_e32 v5, v7, v10
	ds_bpermute_b32 v7, v176, v19
	v_cndmask_b32_e64 v5, v5, -v5, s[6:7]
	v_fmac_f32_e32 v5, v6, v25
	ds_bpermute_b32 v6, v176, v18
	v_cndmask_b32_e64 v13, v21, v13, s[4:5]
	s_waitcnt lgkmcnt(1)
	v_mul_f32_e32 v1, v1, v7
	v_cndmask_b32_e64 v1, v1, -v1, s[6:7]
	v_fmac_f32_e32 v1, v0, v19
	s_waitcnt lgkmcnt(0)
	v_mul_f32_e32 v0, v3, v6
	v_cndmask_b32_e64 v0, v0, -v0, s[6:7]
	v_fmac_f32_e32 v0, v2, v18
	v_cndmask_b32_e64 v3, v18, v0, s[4:5]
	v_cndmask_b32_e64 v9, v16, v9, s[4:5]
	v_cndmask_b32_e64 v5, v25, v5, s[4:5]
	v_cndmask_b32_e64 v7, v19, v1, s[4:5]
	v_cvt_pk_bf16_f32 v0, v12, v13
	v_cvt_pk_bf16_f32 v1, v8, v9
	v_cvt_pk_bf16_f32 v2, v4, v5
	v_cvt_pk_bf16_f32 v3, v7, v3
	flat_store_dwordx4 v[156:157], v[0:3]
	v_lshl_add_u64 v[156:157], v[156:157], 0, s[10:11]
	s_cbranch_scc1 .LBB0_1080

; template <bool NORM, int ROT, bool PERTOK> __device__ __forceinline__ void rope_pass(bf16_t* base, int nchunks, const float* g, const float* tab, float sc, int gw, int NGW, int lane) {
;     constexpr int NB = 8, HALFL = ROT / 16; const int j = lane & 15;
;     for (int it0 = gw * NB; it0 < nchunks; it0 += NGW * NB) {
;         u32x4 w[NB]; f32x4 tb[NB][4];
; #pragma unroll
;         for (int k = 0; k < NB; ++k) { const int it = it0 + k;
;             w[k] = *(const u32x4*)(base + (size_t)it * 512 + lane * 8);
; __device__ __forceinline__ void post_proj(const Args& A, int gw, int NGW, int lane) {
;     ...
;     rope_pass<false, 64, true>((bf16_t*)(ws + WS_IQ), T * 4, nullptr, R2, qs, gw, NGW, lane);
.Lra_1075:
	v_readlane_b32 s91, v255, 3
	s_lshl_b32 s93, s2, 3
	s_add_i32 s93, s93, s91
	s_mov_b32 s94, s44
	s_add_i32 s92, s93, 0x1000
	s_lshr_b32 s96, s92, 3
	s_and_b32 s97, s92, 7
	s_mov_b32 s0, s92
	s_add_u32 s16, s10, 0x800000
	s_addc_u32 s17, s11, 0
	s_andn2_b64 vcc, exec, s[14:15]
	v_and_b32_e32 v122, 4, v179
	v_lshlrev_b32_e32 v123, 2, v179
	s_cbranch_vccnz .Lri_1078
	s_lshl_b32 s14, s0, 3
	s_mov_b32 s3, s97
	s_lshl_b32 s1, s96, 10
	s_lshl_b32 s3, s3, 7
	s_ashr_i32 s15, s14, 31
	s_lshl_b32 s20, s94, 6
	s_add_i32 s1, s1, s3
	s_lshl_b32 s3, s94, 10
	s_lshl_b64 s[22:23], s[14:15], 10
	s_add_u32 s22, s10, s22
	v_ashrrev_i32_e32 v157, 31, v156
	v_and_b32_e32 v0, 0xc0, v180
	v_mov_b32_e32 v1, 0
	s_addc_u32 s23, s11, s23
	v_lshl_add_u64 v[104:105], s[16:17], 0, v[0:1]
	v_lshl_add_u64 v[0:1], v[156:157], 1, s[22:23]
	s_mov_b64 s[22:23], 0x13801c00
	s_ashr_i32 s21, s20, 31
	s_mov_b32 s19, 0
	v_cmp_eq_u32_e64 s[4:5], 0, v181
	v_cmp_eq_u32_e64 s[6:7], 0, v122
	v_xor_b32_e32 v124, 16, v123
	v_lshl_add_u64 v[106:107], v[0:1], 0, s[22:23]
	s_lshl_b64 s[22:23], s[20:21], 10

; template <bool NORM, int ROT, bool PERTOK> __device__ __forceinline__ void rope_pass(bf16_t* base, int nchunks, const float* g, const float* tab, float sc, int gw, int NGW, int lane) {
;     constexpr int NB = 8, HALFL = ROT / 16; const int j = lane & 15;
;     for (int it0 = gw * NB; it0 < nchunks; it0 += NGW * NB) {
;         u32x4 w[NB]; f32x4 tb[NB][4];
; #pragma unroll
;         for (int k = 0; k < NB; ++k) { const int it = it0 + k;
;             w[k] = *(const u32x4*)(base + (size_t)it * 512 + lane * 8);
;             const int pos = PERTOK ? ((it >> 2) & 8191) : (((it * 4) & 8191) + (lane >> 4));
;             const float* tp = tab + (size_t)pos * ROT + (j & (HALFL - 1)) * 16;
; #pragma unroll
;             for (int q = 0; q < 4; ++q) tb[k][q] = *(const f32x4*)(tp + q * 4); }
; __device__ __forceinline__ void post_proj(const Args& A, int gw, int NGW, int lane) {
;     ...
;     rope_pass<true, 64, false>((bf16_t*)(ws + WS_IK), T / 4, A.idx_k_norm_g, R2, 1.f, gw, NGW, lane);
.Lri_1078:
	s_add_i32 s92, s93, 0x100
	s_lshr_b32 s96, s92, 3
	s_and_b32 s97, s92, 7
	s_mov_b32 s0, s92
	s_cmpk_gt_i32 s0, 0x1ff
	s_cbranch_scc1 .Lri_1081
	s_lshl_b32 s14, s0, 3
	v_and_b32_e32 v0, 0xc0, v180
	v_mov_b32_e32 v1, 0
	v_and_b32_e32 v2, 15, v179
	s_mov_b32 s1, s97
	v_lshl_add_u64 v[158:159], s[16:17], 0, v[0:1]
	v_lshlrev_b32_e32 v0, 5, v2
	s_lshl_b32 s0, s96, 8
	s_lshl_b32 s1, s1, 5
	s_ashr_i32 s15, s14, 31
	v_lshl_add_u64 v[160:161], s[12:13], 0, v[0:1]
	s_lshl_b32 s12, s94, 6
	s_add_i32 s0, s0, s1
	s_lshl_b32 s1, s94, 8
	s_lshl_b64 s[16:17], s[14:15], 10
	s_add_u32 s10, s10, s16
	v_ashrrev_i32_e32 v157, 31, v156
	s_addc_u32 s11, s11, s17
	v_lshl_add_u64 v[0:1], v[156:157], 1, s[10:11]
	s_mov_b64 s[10:11], 0xa01c00
	s_ashr_i32 s13, s12, 31
	v_cmp_gt_u32_e64 s[4:5], 8, v2
	v_cmp_eq_u32_e64 s[6:7], 0, v122
	v_xor_b32_e32 v176, 16, v123
	v_lshl_add_u64 v[156:157], v[0:1], 0, s[10:11]
	s_lshl_b64 s[10:11], s[12:13], 10
	s_movk_i32 s3, 0xe800
	s_movk_i32 s13, 0xec00
	s_movk_i32 s15, 0xf000
	s_movk_i32 s16, 0xf400
	s_movk_i32 s17, 0xf800
	s_movk_i32 s18, 0xfc00
	v_mov_b32_e32 v177, 0x358637bd
	s_mov_b32 s19, 0x800000
.Lri_1080:
	v_add_co_u32_e32 v174, vcc, 0xffffe400, v156
	s_and_b32 s20, s0, 0x1fe0
	s_nop 0
	v_addc_co_u32_e32 v175, vcc, -1, v157, vcc
	flat_load_dwordx4 v[0:3], v[174:175]
	v_add_u32_e32 v4, s20, v178
	v_ashrrev_i32_e32 v5, 31, v4
	v_lshlrev_b64 v[4:5], 8, v[4:5]
	s_add_i32 s20, s0, 4
	v_lshl_add_u64 v[4:5], v[158:159], 0, v[4:5]
	s_and_b32 s20, s20, 0x1fe4
	flat_load_dwordx4 v[152:155], v[4:5]
	flat_load_dwordx4 v[148:151], v[4:5] offset:16
	flat_load_dwordx4 v[144:147], v[4:5] offset:32
	flat_load_dwordx4 v[140:143], v[4:5] offset:48
	v_add_u32_e32 v4, s20, v178
	v_ashrrev_i32_e32 v5, 31, v4
	v_add_co_u32_e32 v172, vcc, s3, v156
	v_lshlrev_b64 v[4:5], 8, v[4:5]
	s_add_i32 s20, s0, 8
	v_addc_co_u32_e32 v173, vcc, -1, v157, vcc
	v_lshl_add_u64 v[4:5], v[158:159], 0, v[4:5]
	s_and_b32 s20, s20, 0x1fe8
	flat_load_dwordx4 v[136:139], v[172:173]
	flat_load_dwordx4 v[132:135], v[4:5]
	flat_load_dwordx4 v[128:131], v[4:5] offset:16
	flat_load_dwordx4 v[124:127], v[4:5] offset:32
	flat_load_dwordx4 v[120:123], v[4:5] offset:48
	v_add_u32_e32 v4, s20, v178
	v_ashrrev_i32_e32 v5, 31, v4
	v_add_co_u32_e32 v170, vcc, s13, v156
	v_lshlrev_b64 v[4:5], 8, v[4:5]
	s_add_i32 s20, s0, 12
	v_addc_co_u32_e32 v171, vcc, -1, v157, vcc
	v_lshl_add_u64 v[4:5], v[158:159], 0, v[4:5]
	s_and_b32 s20, s20, 0x1fec
	flat_load_dwordx4 v[116:119], v[170:171]
	flat_load_dwordx4 v[112:115], v[4:5]
	flat_load_dwordx4 v[108:111], v[4:5] offset:16
	flat_load_dwordx4 v[104:107], v[4:5] offset:32
	flat_load_dwordx4 v[100:103], v[4:5] offset:48
	v_add_u32_e32 v4, s20, v178
	v_ashrrev_i32_e32 v5, 31, v4
	v_add_co_u32_e32 v168, vcc, s15, v156
	v_lshlrev_b64 v[4:5], 8, v[4:5]
	s_nop 0
	v_addc_co_u32_e32 v169, vcc, -1, v157, vcc
	v_lshl_add_u64 v[4:5], v[158:159], 0, v[4:5]
	flat_load_dwordx4 v[96:99], v[168:169]
	flat_load_dwordx4 v[92:95], v[4:5]
	flat_load_dwordx4 v[88:91], v[4:5] offset:16
	flat_load_dwordx4 v[84:87], v[4:5] offset:32
	flat_load_dwordx4 v[80:83], v[4:5] offset:48
	flat_load_dwordx4 v[180:183], v[160:161]
	s_add_i32 s20, s0, 16
	s_and_b32 s20, s20, 0x1ff0
	v_add_u32_e32 v4, s20, v178
	v_add_co_u32_e32 v166, vcc, s16, v156
	v_ashrrev_i32_e32 v5, 31, v4
	s_nop 0
	v_addc_co_u32_e32 v167, vcc, -1, v157, vcc
	v_lshlrev_b64 v[4:5], 8, v[4:5]
	flat_load_dwordx4 v[60:63], v[166:167]
	v_lshl_add_u64 v[4:5], v[158:159], 0, v[4:5]
	flat_load_dwordx4 v[184:187], v[160:161] offset:16
	flat_load_dwordx4 v[76:79], v[4:5]
	flat_load_dwordx4 v[72:75], v[4:5] offset:16
	flat_load_dwordx4 v[68:71], v[4:5] offset:32
	flat_load_dwordx4 v[64:67], v[4:5] offset:48
	s_add_i32 s20, s0, 20
	s_and_b32 s20, s20, 0x1ff4
	v_add_u32_e32 v4, s20, v178
	v_ashrrev_i32_e32 v5, 31, v4
	v_add_co_u32_e32 v164, vcc, s17, v156
	v_lshlrev_b64 v[4:5], 8, v[4:5]
	s_add_i32 s20, s0, 24
	v_addc_co_u32_e32 v165, vcc, -1, v157, vcc
	v_lshl_add_u64 v[4:5], v[158:159], 0, v[4:5]
	s_and_b32 s20, s20, 0x1ff8
	flat_load_dwordx4 v[56:59], v[164:165]
	flat_load_dwordx4 v[52:55], v[4:5]
	flat_load_dwordx4 v[48:51], v[4:5] offset:16
	flat_load_dwordx4 v[44:47], v[4:5] offset:32
	flat_load_dwordx4 v[40:43], v[4:5] offset:48
	v_add_u32_e32 v4, s20, v178
	v_ashrrev_i32_e32 v5, 31, v4
	v_add_co_u32_e32 v162, vcc, s18, v156
	v_lshlrev_b64 v[4:5], 8, v[4:5]
	s_add_i32 s20, s0, 28
	v_addc_co_u32_e32 v163, vcc, -1, v157, vcc
	v_lshl_add_u64 v[4:5], v[158:159], 0, v[4:5]
	s_and_b32 s20, s20, 0x1ffc
	flat_load_dwordx4 v[36:39], v[162:163]
	flat_load_dwordx4 v[32:35], v[4:5]
	flat_load_dwordx4 v[28:31], v[4:5] offset:16
	flat_load_dwordx4 v[24:27], v[4:5] offset:32
	flat_load_dwordx4 v[20:23], v[4:5] offset:48
	flat_load_dwordx4 v[16:19], v[156:157]
	v_add_u32_e32 v4, s20, v178
	v_ashrrev_i32_e32 v5, 31, v4
	v_lshlrev_b64 v[4:5], 8, v[4:5]
	s_waitcnt vmcnt(0) lgkmcnt(0)
; __device__ __forceinline__ unsigned cvt_pk_bf16(float lo, float hi) { unsigned r; asm volatile("v_cvt_pk_bf16_f32 %0, %1, %2" : "=v"(r) : "v"(lo), "v"(hi)); return r; }
; __device__ __forceinline__ float shx(float v, int m, int lane) { return __int_as_float(__builtin_amdgcn_ds_bpermute((lane ^ m) << 2, __float_as_int(v))); }
; #define DPPF(v, ctrl) __int_as_float(__builtin_amdgcn_update_dpp(0, __float_as_int(v), (ctrl), 0xf, 0xf, false))
; __device__ __forceinline__ float row16_sum(float x) { x += DPPF(x, 0xB1); x += DPPF(x, 0x4E); x += DPPF(x, 0x141); x += DPPF(x, 0x140); return x; }
; template <bool NORM, int ROT> __device__ __forceinline__ void rope_chunk(bf16_t* p, const u32x4 w, const f32x4 (&tb)[4], const float* g, float sc, int lane) {
;     ...
;         float ss = 0.f;
; #pragma unroll
;         for (int q = 0; q < 8; ++q) ss += x[q] * x[q];
;         ss = row16_sum(ss);
;         const float rstd = rsqrtf(ss * (1.f / 128.f) + EPS);
;         const f32x4 g0 = *(const f32x4*)(g + j * 8), g1 = *(const f32x4*)(g + j * 8 + 4);
; #pragma unroll
;         for (int q = 0; q < 4; ++q) { x[q] *= rstd * g0[q]; x[4 + q] *= rstd * g1[q]; }
;     }
;     constexpr int HALFL = ROT / 16;
;     const bool rot = (ROT == 128) || (j < 8); const bool first = (j & HALFL) == 0;
;     float o[8];
; #pragma unroll
;     for (int q = 0; q < 8; ++q) {
;         const float other = (ROT == 128) ? DPPF(x[q], 0x128)   : shx(x[q], HALFL, lane);
;         const float cs = tb[q >> 1][(q & 1) * 2], sn = tb[q >> 1][(q & 1) * 2 + 1];
;         const float r = first ? (x[q] * cs - other * sn) : (x[q] * cs + other * sn);
;         o[q] = (rot ? r : x[q]) * sc;
;     }
;     u32x4 ow; ow.x = cvt_pk_bf16(o[0], o[1]); ow.y = cvt_pk_bf16(o[2], o[3]); ow.z = cvt_pk_bf16(o[4], o[5]); ow.w = cvt_pk_bf16(o[6], o[7]);
;     *(u32x4*)(p + lane * 8) = ow;
	v_and_b32_e32 v196, 0xffff0000, v0
	v_lshl_add_u64 v[188:189], v[158:159], 0, v[4:5]
	v_lshlrev_b32_e32 v179, 16, v0
	v_mul_f32_e32 v4, v196, v196
	v_and_b32_e32 v190, 0xffff0000, v1
	v_lshlrev_b32_e32 v191, 16, v1
	v_fmac_f32_e32 v4, v179, v179
	v_pk_mul_f32 v[0:1], v[190:191], v[190:191]
	v_and_b32_e32 v192, 0xffff0000, v2
	v_add_f32_e32 v1, v1, v4
	v_lshlrev_b32_e32 v193, 16, v2
	v_add_f32_e32 v4, v0, v1
	v_pk_mul_f32 v[0:1], v[192:193], v[192:193]
	v_and_b32_e32 v194, 0xffff0000, v3
	v_add_f32_e32 v1, v1, v4
	v_lshlrev_b32_e32 v195, 16, v3
	v_add_f32_e32 v2, v0, v1
	v_pk_mul_f32 v[0:1], v[194:195], v[194:195]
	s_add_i32 s14, s14, s12
	v_add_f32_e32 v1, v1, v2
	v_add_f32_e32 v0, v0, v1
	s_add_i32 s0, s0, s1
	s_cmpk_lt_i32 s14, 0x1000
	v_add_f32_dpp v0, v0, v0 quad_perm:[1,0,3,2] row_mask:0xf bank_mask:0xf bound_ctrl:1
	s_nop 1
	v_add_f32_dpp v0, v0, v0 quad_perm:[2,3,0,1] row_mask:0xf bank_mask:0xf bound_ctrl:1
	s_nop 1
	v_add_f32_dpp v0, v0, v0 row_half_mirror row_mask:0xf bank_mask:0xf bound_ctrl:1
	s_nop 1
	v_add_f32_dpp v0, v0, v0 row_mirror row_mask:0xf bank_mask:0xf bound_ctrl:1
	v_fmamk_f32 v0, v0, 0x3c000000, v177
	v_mul_f32_e32 v1, 0x4b800000, v0
	v_cmp_gt_f32_e32 vcc, s19, v0
	s_nop 1
	v_cndmask_b32_e32 v0, v0, v1, vcc
	v_rsq_f32_e32 v197, v0
	flat_load_dwordx4 v[12:15], v[188:189]
	flat_load_dwordx4 v[8:11], v[188:189] offset:16
	flat_load_dwordx4 v[4:7], v[188:189] offset:32
	flat_load_dwordx4 v[0:3], v[188:189] offset:48
	v_mul_f32_e32 v188, 0x45800000, v197
	v_cndmask_b32_e32 v188, v197, v188, vcc
	v_mul_f32_e32 v180, v180, v188
	v_mul_f32_e32 v179, v180, v179
	v_mul_f32_e32 v180, v184, v188
	v_mul_f32_e32 v184, v185, v188
	v_mul_f32_e32 v185, v186, v188
	ds_bpermute_b32 v186, v176, v179
	v_mul_f32_e32 v181, v181, v188
	v_mul_f32_e32 v181, v181, v196
	v_mul_f32_e32 v182, v182, v188
	v_mul_f32_e32 v183, v183, v188
	v_mul_f32_e32 v187, v187, v188
	ds_bpermute_b32 v188, v176, v181
	s_waitcnt lgkmcnt(0)
	v_mul_f32_e32 v153, v153, v186
	v_cndmask_b32_e64 v153, v153, -v153, s[6:7]
	v_mul_f32_e32 v182, v182, v191
	v_fmac_f32_e32 v153, v152, v179
	v_cndmask_b32_e64 v152, v179, v153, s[4:5]
	v_mul_f32_e32 v153, v155, v188
	ds_bpermute_b32 v155, v176, v182
	v_mul_f32_e32 v183, v183, v190
	v_cndmask_b32_e64 v153, v153, -v153, s[6:7]
	v_fmac_f32_e32 v153, v154, v181
	ds_bpermute_b32 v154, v176, v183
	s_waitcnt lgkmcnt(0)
	v_mul_f32_e32 v149, v149, v155
	v_cndmask_b32_e64 v149, v149, -v149, s[6:7]
	v_mul_f32_e32 v180, v180, v193
	v_fmac_f32_e32 v149, v148, v182
	v_cndmask_b32_e64 v148, v182, v149, s[4:5]
	v_mul_f32_e32 v149, v151, v154
	ds_bpermute_b32 v151, v176, v180
	v_mul_f32_e32 v184, v184, v192
	v_cndmask_b32_e64 v149, v149, -v149, s[6:7]
	v_fmac_f32_e32 v149, v150, v183
	ds_bpermute_b32 v150, v176, v184
	s_waitcnt lgkmcnt(0)
	v_mul_f32_e32 v145, v145, v151
	v_cndmask_b32_e64 v145, v145, -v145, s[6:7]
	v_mul_f32_e32 v185, v185, v195
	v_fmac_f32_e32 v145, v144, v180
	v_cndmask_b32_e64 v144, v180, v145, s[4:5]
	v_mul_f32_e32 v145, v147, v150
	ds_bpermute_b32 v147, v176, v185
	v_mul_f32_e32 v187, v187, v194
	v_cndmask_b32_e64 v145, v145, -v145, s[6:7]
	v_fmac_f32_e32 v145, v146, v184
	ds_bpermute_b32 v146, v176, v187
	s_waitcnt lgkmcnt(0)
	v_mul_f32_e32 v141, v141, v147
	v_cndmask_b32_e64 v141, v141, -v141, s[6:7]
	v_fmac_f32_e32 v141, v140, v185
	v_cndmask_b32_e64 v153, v181, v153, s[4:5]
	v_mul_f32_e32 v140, v143, v146
	v_cndmask_b32_e64 v140, v140, -v140, s[6:7]
	v_fmac_f32_e32 v140, v142, v187
	v_cndmask_b32_e64 v143, v187, v140, s[4:5]
	v_cndmask_b32_e64 v149, v183, v149, s[4:5]
	v_cndmask_b32_e64 v145, v184, v145, s[4:5]
	v_cndmask_b32_e64 v147, v185, v141, s[4:5]
	v_cvt_pk_bf16_f32 v140, v152, v153
	v_cvt_pk_bf16_f32 v141, v148, v149
	v_cvt_pk_bf16_f32 v142, v144, v145
	v_cvt_pk_bf16_f32 v143, v147, v143
	flat_store_dwordx4 v[174:175], v[140:143]
	flat_load_dwordx4 v[140:143], v[160:161]
	s_nop 0
	flat_load_dwordx4 v[144:147], v[160:161] offset:16
	v_and_b32_e32 v153, 0xffff0000, v136
	v_lshlrev_b32_e32 v152, 16, v136
	v_mul_f32_e32 v150, v153, v153
	v_and_b32_e32 v136, 0xffff0000, v137
	v_lshlrev_b32_e32 v137, 16, v137
	v_fmac_f32_e32 v150, v152, v152
	v_pk_mul_f32 v[148:149], v[136:137], v[136:137]
	s_nop 0
	v_add_f32_e32 v149, v149, v150
	v_add_f32_e32 v154, v148, v149
	v_and_b32_e32 v148, 0xffff0000, v138
	v_lshlrev_b32_e32 v149, 16, v138
	v_pk_mul_f32 v[150:151], v[148:149], v[148:149]
	s_nop 0
	v_add_f32_e32 v138, v151, v154
	v_add_f32_e32 v154, v150, v138
	v_and_b32_e32 v138, 0xffff0000, v139
	v_lshlrev_b32_e32 v139, 16, v139
	v_pk_mul_f32 v[150:151], v[138:139], v[138:139]
	s_nop 0
	v_add_f32_e32 v151, v151, v154
	v_add_f32_e32 v150, v150, v151
	s_nop 1
	v_add_f32_dpp v150, v150, v150 quad_perm:[1,0,3,2] row_mask:0xf bank_mask:0xf bound_ctrl:1
	s_nop 1
	v_add_f32_dpp v150, v150, v150 quad_perm:[2,3,0,1] row_mask:0xf bank_mask:0xf bound_ctrl:1
	s_nop 1
	v_add_f32_dpp v150, v150, v150 row_half_mirror row_mask:0xf bank_mask:0xf bound_ctrl:1
	s_nop 1
	v_add_f32_dpp v150, v150, v150 row_mirror row_mask:0xf bank_mask:0xf bound_ctrl:1
	v_fmamk_f32 v150, v150, 0x3c000000, v177
	v_mul_f32_e32 v151, 0x4b800000, v150
	v_cmp_gt_f32_e32 vcc, s19, v150
	s_nop 1
	v_cndmask_b32_e32 v150, v150, v151, vcc
	v_rsq_f32_e32 v150, v150
	s_nop 0
	v_mul_f32_e32 v151, 0x45800000, v150
	v_cndmask_b32_e32 v150, v150, v151, vcc
	s_waitcnt vmcnt(0) lgkmcnt(0)
	v_mul_f32_e32 v140, v140, v150
	v_mul_f32_e32 v142, v142, v150
	v_mul_f32_e32 v140, v140, v152
	v_mul_f32_e32 v137, v142, v137
	v_mul_f32_e32 v142, v146, v150
	v_mul_f32_e32 v139, v142, v139
	v_mul_f32_e32 v142, v143, v150
	ds_bpermute_b32 v143, v176, v140
	v_mul_f32_e32 v141, v141, v150
	v_mul_f32_e32 v141, v141, v153
	v_mul_f32_e32 v136, v142, v136
	v_mul_f32_e32 v142, v147, v150
	v_mul_f32_e32 v138, v142, v138
	ds_bpermute_b32 v142, v176, v141
	s_waitcnt lgkmcnt(1)
; __device__ __forceinline__ unsigned cvt_pk_bf16(float lo, float hi) { unsigned r; asm volatile("v_cvt_pk_bf16_f32 %0, %1, %2" : "=v"(r) : "v"(lo), "v"(hi)); return r; }
; __device__ __forceinline__ float shx(float v, int m, int lane) { return __int_as_float(__builtin_amdgcn_ds_bpermute((lane ^ m) << 2, __float_as_int(v))); }
; #define DPPF(v, ctrl) __int_as_float(__builtin_amdgcn_update_dpp(0, __float_as_int(v), (ctrl), 0xf, 0xf, false))
; __device__ __forceinline__ float row16_sum(float x) { x += DPPF(x, 0xB1); x += DPPF(x, 0x4E); x += DPPF(x, 0x141); x += DPPF(x, 0x140); return x; }
; template <bool NORM, int ROT> __device__ __forceinline__ void rope_chunk(bf16_t* p, const u32x4 w, const f32x4 (&tb)[4], const float* g, float sc, int lane) {
;     ...
;         float ss = 0.f;
; #pragma unroll
;         for (int q = 0; q < 8; ++q) ss += x[q] * x[q];
;         ss = row16_sum(ss);
;         const float rstd = rsqrtf(ss * (1.f / 128.f) + EPS);
;         const f32x4 g0 = *(const f32x4*)(g + j * 8), g1 = *(const f32x4*)(g + j * 8 + 4);
; #pragma unroll
;         for (int q = 0; q < 4; ++q) { x[q] *= rstd * g0[q]; x[4 + q] *= rstd * g1[q]; }
;     }
;     constexpr int HALFL = ROT / 16;
;     const bool rot = (ROT == 128) || (j < 8); const bool first = (j & HALFL) == 0;
;     float o[8];
; #pragma unroll
;     for (int q = 0; q < 8; ++q) {
;         const float other = (ROT == 128) ? DPPF(x[q], 0x128)   : shx(x[q], HALFL, lane);
;         const float cs = tb[q >> 1][(q & 1) * 2], sn = tb[q >> 1][(q & 1) * 2 + 1];
;         const float r = first ? (x[q] * cs - other * sn) : (x[q] * cs + other * sn);
;         o[q] = (rot ? r : x[q]) * sc;
;     }
;     u32x4 ow; ow.x = cvt_pk_bf16(o[0], o[1]); ow.y = cvt_pk_bf16(o[2], o[3]); ow.z = cvt_pk_bf16(o[4], o[5]); ow.w = cvt_pk_bf16(o[6], o[7]);
;     *(u32x4*)(p + lane * 8) = ow;
	v_mul_f32_e32 v133, v133, v143
	v_cndmask_b32_e64 v133, v133, -v133, s[6:7]
	v_fmac_f32_e32 v133, v132, v140
	v_cndmask_b32_e64 v132, v140, v133, s[4:5]
	s_waitcnt lgkmcnt(0)
	v_mul_f32_e32 v133, v135, v142
	ds_bpermute_b32 v135, v176, v137
	v_cndmask_b32_e64 v133, v133, -v133, s[6:7]
	v_fmac_f32_e32 v133, v134, v141
	ds_bpermute_b32 v134, v176, v136
	v_mul_f32_e32 v144, v144, v150
	s_waitcnt lgkmcnt(1)
	v_mul_f32_e32 v129, v129, v135
	v_cndmask_b32_e64 v129, v129, -v129, s[6:7]
	v_mul_f32_e32 v144, v144, v149
	v_fmac_f32_e32 v129, v128, v137
	v_cndmask_b32_e64 v128, v137, v129, s[4:5]
	s_waitcnt lgkmcnt(0)
	v_mul_f32_e32 v129, v131, v134
	ds_bpermute_b32 v131, v176, v144
	v_mul_f32_e32 v145, v145, v150
	v_mul_f32_e32 v145, v145, v148
	v_cndmask_b32_e64 v129, v129, -v129, s[6:7]
	v_fmac_f32_e32 v129, v130, v136
	ds_bpermute_b32 v130, v176, v145
	s_waitcnt lgkmcnt(1)
	v_mul_f32_e32 v125, v125, v131
	v_cndmask_b32_e64 v125, v125, -v125, s[6:7]
	v_fmac_f32_e32 v125, v124, v144
	v_cndmask_b32_e64 v124, v144, v125, s[4:5]
	s_waitcnt lgkmcnt(0)
	v_mul_f32_e32 v125, v127, v130
	ds_bpermute_b32 v127, v176, v139
	v_cndmask_b32_e64 v125, v125, -v125, s[6:7]
	v_fmac_f32_e32 v125, v126, v145
	ds_bpermute_b32 v126, v176, v138
	v_cndmask_b32_e64 v133, v141, v133, s[4:5]
	s_waitcnt lgkmcnt(1)
	v_mul_f32_e32 v121, v121, v127
	v_cndmask_b32_e64 v121, v121, -v121, s[6:7]
	v_fmac_f32_e32 v121, v120, v139
	s_waitcnt lgkmcnt(0)
	v_mul_f32_e32 v120, v123, v126
	v_cndmask_b32_e64 v120, v120, -v120, s[6:7]
	v_fmac_f32_e32 v120, v122, v138
	v_cndmask_b32_e64 v123, v138, v120, s[4:5]
	v_cndmask_b32_e64 v129, v136, v129, s[4:5]
	v_cndmask_b32_e64 v125, v145, v125, s[4:5]
	v_cndmask_b32_e64 v127, v139, v121, s[4:5]
	v_cvt_pk_bf16_f32 v120, v132, v133
	v_cvt_pk_bf16_f32 v121, v128, v129
	v_cvt_pk_bf16_f32 v122, v124, v125
	v_cvt_pk_bf16_f32 v123, v127, v123
	flat_store_dwordx4 v[172:173], v[120:123]
	flat_load_dwordx4 v[120:123], v[160:161]
	s_nop 0
	flat_load_dwordx4 v[124:127], v[160:161] offset:16
	v_and_b32_e32 v133, 0xffff0000, v116
	v_lshlrev_b32_e32 v132, 16, v116
	v_mul_f32_e32 v130, v133, v133
	v_and_b32_e32 v116, 0xffff0000, v117
	v_lshlrev_b32_e32 v117, 16, v117
	v_fmac_f32_e32 v130, v132, v132
	v_pk_mul_f32 v[128:129], v[116:117], v[116:117]
	s_nop 0
	v_add_f32_e32 v129, v129, v130
	v_add_f32_e32 v134, v128, v129
	v_and_b32_e32 v128, 0xffff0000, v118
	v_lshlrev_b32_e32 v129, 16, v118
	v_pk_mul_f32 v[130:131], v[128:129], v[128:129]
	s_nop 0
	v_add_f32_e32 v118, v131, v134
	v_add_f32_e32 v134, v130, v118
	v_and_b32_e32 v118, 0xffff0000, v119
	v_lshlrev_b32_e32 v119, 16, v119
	v_pk_mul_f32 v[130:131], v[118:119], v[118:119]
	s_nop 0
	v_add_f32_e32 v131, v131, v134
	v_add_f32_e32 v130, v130, v131
	s_nop 1
	v_add_f32_dpp v130, v130, v130 quad_perm:[1,0,3,2] row_mask:0xf bank_mask:0xf bound_ctrl:1
	s_nop 1
	v_add_f32_dpp v130, v130, v130 quad_perm:[2,3,0,1] row_mask:0xf bank_mask:0xf bound_ctrl:1
	s_nop 1
	v_add_f32_dpp v130, v130, v130 row_half_mirror row_mask:0xf bank_mask:0xf bound_ctrl:1
	s_nop 1
	v_add_f32_dpp v130, v130, v130 row_mirror row_mask:0xf bank_mask:0xf bound_ctrl:1
	v_fmamk_f32 v130, v130, 0x3c000000, v177
	v_mul_f32_e32 v131, 0x4b800000, v130
	v_cmp_gt_f32_e32 vcc, s19, v130
	s_nop 1
	v_cndmask_b32_e32 v130, v130, v131, vcc
	v_rsq_f32_e32 v130, v130
	s_nop 0
	v_mul_f32_e32 v131, 0x45800000, v130
	v_cndmask_b32_e32 v130, v130, v131, vcc
	s_waitcnt vmcnt(0) lgkmcnt(0)
	v_mul_f32_e32 v120, v120, v130
	v_mul_f32_e32 v122, v122, v130
	v_mul_f32_e32 v120, v120, v132
	v_mul_f32_e32 v117, v122, v117
	v_mul_f32_e32 v122, v126, v130
	v_mul_f32_e32 v119, v122, v119
	v_mul_f32_e32 v122, v123, v130
	ds_bpermute_b32 v123, v176, v120
	v_mul_f32_e32 v121, v121, v130
	v_mul_f32_e32 v121, v121, v133
	v_mul_f32_e32 v116, v122, v116
	v_mul_f32_e32 v122, v127, v130
	v_mul_f32_e32 v118, v122, v118
	ds_bpermute_b32 v122, v176, v121
	s_waitcnt lgkmcnt(1)
	v_mul_f32_e32 v113, v113, v123
	v_cndmask_b32_e64 v113, v113, -v113, s[6:7]
	v_fmac_f32_e32 v113, v112, v120
	v_cndmask_b32_e64 v112, v120, v113, s[4:5]
	s_waitcnt lgkmcnt(0)
	v_mul_f32_e32 v113, v115, v122
	ds_bpermute_b32 v115, v176, v117
	v_cndmask_b32_e64 v113, v113, -v113, s[6:7]
	v_fmac_f32_e32 v113, v114, v121
	ds_bpermute_b32 v114, v176, v116
	v_mul_f32_e32 v124, v124, v130
	s_waitcnt lgkmcnt(1)
	v_mul_f32_e32 v109, v109, v115
	v_cndmask_b32_e64 v109, v109, -v109, s[6:7]
	v_mul_f32_e32 v124, v124, v129
	v_fmac_f32_e32 v109, v108, v117
	v_cndmask_b32_e64 v108, v117, v109, s[4:5]
	s_waitcnt lgkmcnt(0)
	v_mul_f32_e32 v109, v111, v114
	ds_bpermute_b32 v111, v176, v124
	v_mul_f32_e32 v125, v125, v130
	v_mul_f32_e32 v125, v125, v128
	v_cndmask_b32_e64 v109, v109, -v109, s[6:7]
	v_fmac_f32_e32 v109, v110, v116
	ds_bpermute_b32 v110, v176, v125
	s_waitcnt lgkmcnt(1)
	v_mul_f32_e32 v105, v105, v111
	v_cndmask_b32_e64 v105, v105, -v105, s[6:7]
	v_fmac_f32_e32 v105, v104, v124
	v_cndmask_b32_e64 v104, v124, v105, s[4:5]
	s_waitcnt lgkmcnt(0)
	v_mul_f32_e32 v105, v107, v110
	ds_bpermute_b32 v107, v176, v119
	v_cndmask_b32_e64 v105, v105, -v105, s[6:7]
	v_fmac_f32_e32 v105, v106, v125
	ds_bpermute_b32 v106, v176, v118
	v_cndmask_b32_e64 v113, v121, v113, s[4:5]
	s_waitcnt lgkmcnt(1)
	v_mul_f32_e32 v101, v101, v107
	v_cndmask_b32_e64 v101, v101, -v101, s[6:7]
	v_fmac_f32_e32 v101, v100, v119
	s_waitcnt lgkmcnt(0)
; __device__ __forceinline__ unsigned cvt_pk_bf16(float lo, float hi) { unsigned r; asm volatile("v_cvt_pk_bf16_f32 %0, %1, %2" : "=v"(r) : "v"(lo), "v"(hi)); return r; }
; __device__ __forceinline__ float shx(float v, int m, int lane) { return __int_as_float(__builtin_amdgcn_ds_bpermute((lane ^ m) << 2, __float_as_int(v))); }
; #define DPPF(v, ctrl) __int_as_float(__builtin_amdgcn_update_dpp(0, __float_as_int(v), (ctrl), 0xf, 0xf, false))
; __device__ __forceinline__ float row16_sum(float x) { x += DPPF(x, 0xB1); x += DPPF(x, 0x4E); x += DPPF(x, 0x141); x += DPPF(x, 0x140); return x; }
; template <bool NORM, int ROT> __device__ __forceinline__ void rope_chunk(bf16_t* p, const u32x4 w, const f32x4 (&tb)[4], const float* g, float sc, int lane) {
;     ...
;         float ss = 0.f;
; #pragma unroll
;         for (int q = 0; q < 8; ++q) ss += x[q] * x[q];
;         ss = row16_sum(ss);
;         const float rstd = rsqrtf(ss * (1.f / 128.f) + EPS);
;         const f32x4 g0 = *(const f32x4*)(g + j * 8), g1 = *(const f32x4*)(g + j * 8 + 4);
; #pragma unroll
;         for (int q = 0; q < 4; ++q) { x[q] *= rstd * g0[q]; x[4 + q] *= rstd * g1[q]; }
;     }
;     constexpr int HALFL = ROT / 16;
;     const bool rot = (ROT == 128) || (j < 8); const bool first = (j & HALFL) == 0;
;     float o[8];
; #pragma unroll
;     for (int q = 0; q < 8; ++q) {
;         const float other = (ROT == 128) ? DPPF(x[q], 0x128)   : shx(x[q], HALFL, lane);
;         const float cs = tb[q >> 1][(q & 1) * 2], sn = tb[q >> 1][(q & 1) * 2 + 1];
;         const float r = first ? (x[q] * cs - other * sn) : (x[q] * cs + other * sn);
;         o[q] = (rot ? r : x[q]) * sc;
;     }
;     u32x4 ow; ow.x = cvt_pk_bf16(o[0], o[1]); ow.y = cvt_pk_bf16(o[2], o[3]); ow.z = cvt_pk_bf16(o[4], o[5]); ow.w = cvt_pk_bf16(o[6], o[7]);
;     *(u32x4*)(p + lane * 8) = ow;
	v_mul_f32_e32 v100, v103, v106
	v_cndmask_b32_e64 v100, v100, -v100, s[6:7]
	v_fmac_f32_e32 v100, v102, v118
	v_cndmask_b32_e64 v103, v118, v100, s[4:5]
	v_cndmask_b32_e64 v109, v116, v109, s[4:5]
	v_cndmask_b32_e64 v105, v125, v105, s[4:5]
	v_cndmask_b32_e64 v107, v119, v101, s[4:5]
	v_cvt_pk_bf16_f32 v100, v112, v113
	v_cvt_pk_bf16_f32 v101, v108, v109
	v_cvt_pk_bf16_f32 v102, v104, v105
	v_cvt_pk_bf16_f32 v103, v107, v103
	flat_store_dwordx4 v[170:171], v[100:103]
	flat_load_dwordx4 v[100:103], v[160:161]
	s_nop 0
	flat_load_dwordx4 v[104:107], v[160:161] offset:16
	v_and_b32_e32 v113, 0xffff0000, v96
	v_lshlrev_b32_e32 v112, 16, v96
	v_mul_f32_e32 v110, v113, v113
	v_and_b32_e32 v96, 0xffff0000, v97
	v_lshlrev_b32_e32 v97, 16, v97
	v_fmac_f32_e32 v110, v112, v112
	v_pk_mul_f32 v[108:109], v[96:97], v[96:97]
	s_nop 0
	v_add_f32_e32 v109, v109, v110
	v_add_f32_e32 v114, v108, v109
	v_and_b32_e32 v108, 0xffff0000, v98
	v_lshlrev_b32_e32 v109, 16, v98
	v_pk_mul_f32 v[110:111], v[108:109], v[108:109]
	s_nop 0
	v_add_f32_e32 v98, v111, v114
	v_add_f32_e32 v114, v110, v98
	v_and_b32_e32 v98, 0xffff0000, v99
	v_lshlrev_b32_e32 v99, 16, v99
	v_pk_mul_f32 v[110:111], v[98:99], v[98:99]
	s_nop 0
	v_add_f32_e32 v111, v111, v114
	v_add_f32_e32 v110, v110, v111
	s_nop 1
	v_add_f32_dpp v110, v110, v110 quad_perm:[1,0,3,2] row_mask:0xf bank_mask:0xf bound_ctrl:1
	s_nop 1
	v_add_f32_dpp v110, v110, v110 quad_perm:[2,3,0,1] row_mask:0xf bank_mask:0xf bound_ctrl:1
	s_nop 1
	v_add_f32_dpp v110, v110, v110 row_half_mirror row_mask:0xf bank_mask:0xf bound_ctrl:1
	s_nop 1
	v_add_f32_dpp v110, v110, v110 row_mirror row_mask:0xf bank_mask:0xf bound_ctrl:1
	v_fmamk_f32 v110, v110, 0x3c000000, v177
	v_mul_f32_e32 v111, 0x4b800000, v110
	v_cmp_gt_f32_e32 vcc, s19, v110
	s_nop 1
	v_cndmask_b32_e32 v110, v110, v111, vcc
	v_rsq_f32_e32 v110, v110
	s_nop 0
	v_mul_f32_e32 v111, 0x45800000, v110
	v_cndmask_b32_e32 v110, v110, v111, vcc
	s_waitcnt vmcnt(0) lgkmcnt(0)
	v_mul_f32_e32 v100, v100, v110
	v_mul_f32_e32 v102, v102, v110
	v_mul_f32_e32 v100, v100, v112
	v_mul_f32_e32 v97, v102, v97
	v_mul_f32_e32 v102, v106, v110
	v_mul_f32_e32 v99, v102, v99
	v_mul_f32_e32 v102, v103, v110
	ds_bpermute_b32 v103, v176, v100
	v_mul_f32_e32 v101, v101, v110
	v_mul_f32_e32 v101, v101, v113
	v_mul_f32_e32 v96, v102, v96
	v_mul_f32_e32 v102, v107, v110
	v_mul_f32_e32 v98, v102, v98
	ds_bpermute_b32 v102, v176, v101
	s_waitcnt lgkmcnt(1)
	v_mul_f32_e32 v93, v93, v103
	v_cndmask_b32_e64 v93, v93, -v93, s[6:7]
	v_fmac_f32_e32 v93, v92, v100
	v_cndmask_b32_e64 v92, v100, v93, s[4:5]
	s_waitcnt lgkmcnt(0)
	v_mul_f32_e32 v93, v95, v102
	ds_bpermute_b32 v95, v176, v97
	v_cndmask_b32_e64 v93, v93, -v93, s[6:7]
	v_fmac_f32_e32 v93, v94, v101
	ds_bpermute_b32 v94, v176, v96
	v_mul_f32_e32 v104, v104, v110
	s_waitcnt lgkmcnt(1)
	v_mul_f32_e32 v89, v89, v95
	v_cndmask_b32_e64 v89, v89, -v89, s[6:7]
	v_mul_f32_e32 v104, v104, v109
	v_fmac_f32_e32 v89, v88, v97
	v_cndmask_b32_e64 v88, v97, v89, s[4:5]
	s_waitcnt lgkmcnt(0)
	v_mul_f32_e32 v89, v91, v94
	ds_bpermute_b32 v91, v176, v104
	v_mul_f32_e32 v105, v105, v110
	v_mul_f32_e32 v105, v105, v108
	v_cndmask_b32_e64 v89, v89, -v89, s[6:7]
	v_fmac_f32_e32 v89, v90, v96
	ds_bpermute_b32 v90, v176, v105
	s_waitcnt lgkmcnt(1)
	v_mul_f32_e32 v85, v85, v91
	v_cndmask_b32_e64 v85, v85, -v85, s[6:7]
	v_fmac_f32_e32 v85, v84, v104
	v_cndmask_b32_e64 v84, v104, v85, s[4:5]
	s_waitcnt lgkmcnt(0)
	v_mul_f32_e32 v85, v87, v90
	ds_bpermute_b32 v87, v176, v99
	v_cndmask_b32_e64 v85, v85, -v85, s[6:7]
	v_fmac_f32_e32 v85, v86, v105
	ds_bpermute_b32 v86, v176, v98
	v_cndmask_b32_e64 v93, v101, v93, s[4:5]
	s_waitcnt lgkmcnt(1)
	v_mul_f32_e32 v81, v81, v87
	v_cndmask_b32_e64 v81, v81, -v81, s[6:7]
	v_fmac_f32_e32 v81, v80, v99
	s_waitcnt lgkmcnt(0)
	v_mul_f32_e32 v80, v83, v86
	v_cndmask_b32_e64 v80, v80, -v80, s[6:7]
	v_fmac_f32_e32 v80, v82, v98
	v_cndmask_b32_e64 v83, v98, v80, s[4:5]
	v_cndmask_b32_e64 v89, v96, v89, s[4:5]
	v_cndmask_b32_e64 v85, v105, v85, s[4:5]
	v_cndmask_b32_e64 v87, v99, v81, s[4:5]
	v_cvt_pk_bf16_f32 v80, v92, v93
	v_cvt_pk_bf16_f32 v81, v88, v89
	v_cvt_pk_bf16_f32 v82, v84, v85
	v_cvt_pk_bf16_f32 v83, v87, v83
	flat_store_dwordx4 v[168:169], v[80:83]
	flat_load_dwordx4 v[80:83], v[160:161]
	s_nop 0
	flat_load_dwordx4 v[84:87], v[160:161] offset:16
	v_and_b32_e32 v93, 0xffff0000, v60
	v_lshlrev_b32_e32 v92, 16, v60
	v_mul_f32_e32 v90, v93, v93
	v_and_b32_e32 v60, 0xffff0000, v61
	v_lshlrev_b32_e32 v61, 16, v61
	v_fmac_f32_e32 v90, v92, v92
	v_pk_mul_f32 v[88:89], v[60:61], v[60:61]
	s_nop 0
	v_add_f32_e32 v89, v89, v90
	v_add_f32_e32 v94, v88, v89
	v_and_b32_e32 v88, 0xffff0000, v62
	v_lshlrev_b32_e32 v89, 16, v62
	v_pk_mul_f32 v[90:91], v[88:89], v[88:89]
	s_nop 0
	v_add_f32_e32 v62, v91, v94
	v_add_f32_e32 v94, v90, v62
	v_and_b32_e32 v62, 0xffff0000, v63
	v_lshlrev_b32_e32 v63, 16, v63
	v_pk_mul_f32 v[90:91], v[62:63], v[62:63]
	s_nop 0
	v_add_f32_e32 v91, v91, v94
	v_add_f32_e32 v90, v90, v91
	s_nop 1
	v_add_f32_dpp v90, v90, v90 quad_perm:[1,0,3,2] row_mask:0xf bank_mask:0xf bound_ctrl:1
	s_nop 1
	v_add_f32_dpp v90, v90, v90 quad_perm:[2,3,0,1] row_mask:0xf bank_mask:0xf bound_ctrl:1
	s_nop 1
	v_add_f32_dpp v90, v90, v90 row_half_mirror row_mask:0xf bank_mask:0xf bound_ctrl:1
	s_nop 1
	v_add_f32_dpp v90, v90, v90 row_mirror row_mask:0xf bank_mask:0xf bound_ctrl:1
	v_fmamk_f32 v90, v90, 0x3c000000, v177
	v_mul_f32_e32 v91, 0x4b800000, v90
	v_cmp_gt_f32_e32 vcc, s19, v90
	s_nop 1
	v_cndmask_b32_e32 v90, v90, v91, vcc
	v_rsq_f32_e32 v90, v90
	s_nop 0
	v_mul_f32_e32 v91, 0x45800000, v90
	v_cndmask_b32_e32 v90, v90, v91, vcc
	s_waitcnt vmcnt(0) lgkmcnt(0)
; __device__ __forceinline__ unsigned cvt_pk_bf16(float lo, float hi) { unsigned r; asm volatile("v_cvt_pk_bf16_f32 %0, %1, %2" : "=v"(r) : "v"(lo), "v"(hi)); return r; }
; __device__ __forceinline__ float shx(float v, int m, int lane) { return __int_as_float(__builtin_amdgcn_ds_bpermute((lane ^ m) << 2, __float_as_int(v))); }
; #define DPPF(v, ctrl) __int_as_float(__builtin_amdgcn_update_dpp(0, __float_as_int(v), (ctrl), 0xf, 0xf, false))
; __device__ __forceinline__ float row16_sum(float x) { x += DPPF(x, 0xB1); x += DPPF(x, 0x4E); x += DPPF(x, 0x141); x += DPPF(x, 0x140); return x; }
; template <bool NORM, int ROT> __device__ __forceinline__ void rope_chunk(bf16_t* p, const u32x4 w, const f32x4 (&tb)[4], const float* g, float sc, int lane) {
;     ...
;         float ss = 0.f;
; #pragma unroll
;         for (int q = 0; q < 8; ++q) ss += x[q] * x[q];
;         ss = row16_sum(ss);
;         const float rstd = rsqrtf(ss * (1.f / 128.f) + EPS);
;         const f32x4 g0 = *(const f32x4*)(g + j * 8), g1 = *(const f32x4*)(g + j * 8 + 4);
; #pragma unroll
;         for (int q = 0; q < 4; ++q) { x[q] *= rstd * g0[q]; x[4 + q] *= rstd * g1[q]; }
;     }
;     constexpr int HALFL = ROT / 16;
;     const bool rot = (ROT == 128) || (j < 8); const bool first = (j & HALFL) == 0;
;     float o[8];
; #pragma unroll
;     for (int q = 0; q < 8; ++q) {
;         const float other = (ROT == 128) ? DPPF(x[q], 0x128)   : shx(x[q], HALFL, lane);
;         const float cs = tb[q >> 1][(q & 1) * 2], sn = tb[q >> 1][(q & 1) * 2 + 1];
;         const float r = first ? (x[q] * cs - other * sn) : (x[q] * cs + other * sn);
;         o[q] = (rot ? r : x[q]) * sc;
;     }
;     u32x4 ow; ow.x = cvt_pk_bf16(o[0], o[1]); ow.y = cvt_pk_bf16(o[2], o[3]); ow.z = cvt_pk_bf16(o[4], o[5]); ow.w = cvt_pk_bf16(o[6], o[7]);
;     *(u32x4*)(p + lane * 8) = ow;
	v_mul_f32_e32 v80, v80, v90
	v_mul_f32_e32 v82, v82, v90
	v_mul_f32_e32 v80, v80, v92
	v_mul_f32_e32 v61, v82, v61
	v_mul_f32_e32 v82, v86, v90
	v_mul_f32_e32 v63, v82, v63
	v_mul_f32_e32 v82, v83, v90
	ds_bpermute_b32 v83, v176, v80
	v_mul_f32_e32 v81, v81, v90
	v_mul_f32_e32 v81, v81, v93
	v_mul_f32_e32 v60, v82, v60
	v_mul_f32_e32 v82, v87, v90
	v_mul_f32_e32 v62, v82, v62
	ds_bpermute_b32 v82, v176, v81
	s_waitcnt lgkmcnt(1)
	v_mul_f32_e32 v77, v77, v83
	v_cndmask_b32_e64 v77, v77, -v77, s[6:7]
	v_fmac_f32_e32 v77, v76, v80
	v_cndmask_b32_e64 v76, v80, v77, s[4:5]
	s_waitcnt lgkmcnt(0)
	v_mul_f32_e32 v77, v79, v82
	ds_bpermute_b32 v79, v176, v61
	v_cndmask_b32_e64 v77, v77, -v77, s[6:7]
	v_fmac_f32_e32 v77, v78, v81
	ds_bpermute_b32 v78, v176, v60
	v_mul_f32_e32 v84, v84, v90
	s_waitcnt lgkmcnt(1)
	v_mul_f32_e32 v73, v73, v79
	v_cndmask_b32_e64 v73, v73, -v73, s[6:7]
	v_fmac_f32_e32 v73, v72, v61
	s_waitcnt lgkmcnt(0)
	v_mul_f32_e32 v72, v75, v78
	v_mul_f32_e32 v84, v84, v89
	v_mul_f32_e32 v85, v85, v90
	v_cndmask_b32_e64 v72, v72, -v72, s[6:7]
	v_mul_f32_e32 v85, v85, v88
	v_cndmask_b32_e64 v61, v61, v73, s[4:5]
	ds_bpermute_b32 v73, v176, v84
	v_fmac_f32_e32 v72, v74, v60
	v_cndmask_b32_e64 v72, v60, v72, s[4:5]
	ds_bpermute_b32 v60, v176, v85
	v_cndmask_b32_e64 v77, v81, v77, s[4:5]
	s_waitcnt lgkmcnt(1)
	v_mul_f32_e32 v69, v69, v73
	v_cndmask_b32_e64 v69, v69, -v69, s[6:7]
	v_fmac_f32_e32 v69, v68, v84
	s_waitcnt lgkmcnt(0)
	v_mul_f32_e32 v60, v71, v60
	v_cndmask_b32_e64 v60, v60, -v60, s[6:7]
	v_cndmask_b32_e64 v68, v84, v69, s[4:5]
	ds_bpermute_b32 v69, v176, v63
	v_fmac_f32_e32 v60, v70, v85
	v_cndmask_b32_e64 v70, v85, v60, s[4:5]
	ds_bpermute_b32 v60, v176, v62
	v_and_b32_e32 v73, 0xffff0000, v56
	s_waitcnt lgkmcnt(1)
	v_mul_f32_e32 v65, v65, v69
	v_cndmask_b32_e64 v65, v65, -v65, s[6:7]
	v_fmac_f32_e32 v65, v64, v63
	s_waitcnt lgkmcnt(0)
	v_mul_f32_e32 v60, v67, v60
	v_cndmask_b32_e64 v60, v60, -v60, s[6:7]
	v_cndmask_b32_e64 v63, v63, v65, s[4:5]
	v_fmac_f32_e32 v60, v66, v62
	v_cndmask_b32_e64 v64, v62, v60, s[4:5]
	v_cvt_pk_bf16_f32 v60, v76, v77
	v_cvt_pk_bf16_f32 v61, v61, v72
	v_cvt_pk_bf16_f32 v62, v68, v70
	v_cvt_pk_bf16_f32 v63, v63, v64
	flat_store_dwordx4 v[166:167], v[60:63]
	flat_load_dwordx4 v[60:63], v[160:161]
	s_nop 0
	flat_load_dwordx4 v[64:67], v[160:161] offset:16
	v_lshlrev_b32_e32 v72, 16, v56
	v_mul_f32_e32 v70, v73, v73
	v_and_b32_e32 v56, 0xffff0000, v57
	v_lshlrev_b32_e32 v57, 16, v57
	v_fmac_f32_e32 v70, v72, v72
	v_pk_mul_f32 v[68:69], v[56:57], v[56:57]
	s_nop 0
	v_add_f32_e32 v69, v69, v70
	v_add_f32_e32 v74, v68, v69
	v_and_b32_e32 v68, 0xffff0000, v58
	v_lshlrev_b32_e32 v69, 16, v58
	v_pk_mul_f32 v[70:71], v[68:69], v[68:69]
	s_nop 0
	v_add_f32_e32 v58, v71, v74
	v_add_f32_e32 v74, v70, v58
	v_and_b32_e32 v58, 0xffff0000, v59
	v_lshlrev_b32_e32 v59, 16, v59
	v_pk_mul_f32 v[70:71], v[58:59], v[58:59]
	s_nop 0
	v_add_f32_e32 v71, v71, v74
	v_add_f32_e32 v70, v70, v71
	s_nop 1
	v_add_f32_dpp v70, v70, v70 quad_perm:[1,0,3,2] row_mask:0xf bank_mask:0xf bound_ctrl:1
	s_nop 1
	v_add_f32_dpp v70, v70, v70 quad_perm:[2,3,0,1] row_mask:0xf bank_mask:0xf bound_ctrl:1
	s_nop 1
	v_add_f32_dpp v70, v70, v70 row_half_mirror row_mask:0xf bank_mask:0xf bound_ctrl:1
	s_nop 1
	v_add_f32_dpp v70, v70, v70 row_mirror row_mask:0xf bank_mask:0xf bound_ctrl:1
	v_fmamk_f32 v70, v70, 0x3c000000, v177
	v_mul_f32_e32 v71, 0x4b800000, v70
	v_cmp_gt_f32_e32 vcc, s19, v70
	s_nop 1
	v_cndmask_b32_e32 v70, v70, v71, vcc
	v_rsq_f32_e32 v70, v70
	s_nop 0
	v_mul_f32_e32 v71, 0x45800000, v70
	v_cndmask_b32_e32 v70, v70, v71, vcc
	s_waitcnt vmcnt(0) lgkmcnt(0)
	v_mul_f32_e32 v60, v60, v70
	v_mul_f32_e32 v62, v62, v70
	v_mul_f32_e32 v60, v60, v72
	v_mul_f32_e32 v57, v62, v57
	v_mul_f32_e32 v62, v66, v70
	v_mul_f32_e32 v59, v62, v59
	v_mul_f32_e32 v62, v63, v70
	ds_bpermute_b32 v63, v176, v60
	v_mul_f32_e32 v61, v61, v70
	v_mul_f32_e32 v61, v61, v73
	v_mul_f32_e32 v56, v62, v56
	v_mul_f32_e32 v62, v67, v70
	v_mul_f32_e32 v58, v62, v58
	ds_bpermute_b32 v62, v176, v61
	s_waitcnt lgkmcnt(1)
	v_mul_f32_e32 v53, v53, v63
	v_cndmask_b32_e64 v53, v53, -v53, s[6:7]
	v_fmac_f32_e32 v53, v52, v60
	v_cndmask_b32_e64 v52, v60, v53, s[4:5]
	s_waitcnt lgkmcnt(0)
	v_mul_f32_e32 v53, v55, v62
	ds_bpermute_b32 v55, v176, v57
	v_cndmask_b32_e64 v53, v53, -v53, s[6:7]
	v_fmac_f32_e32 v53, v54, v61
	ds_bpermute_b32 v54, v176, v56
	v_mul_f32_e32 v64, v64, v70
	s_waitcnt lgkmcnt(1)
	v_mul_f32_e32 v49, v49, v55
	v_cndmask_b32_e64 v49, v49, -v49, s[6:7]
	v_mul_f32_e32 v64, v64, v69
	v_fmac_f32_e32 v49, v48, v57
	v_cndmask_b32_e64 v48, v57, v49, s[4:5]
	s_waitcnt lgkmcnt(0)
	v_mul_f32_e32 v49, v51, v54
	ds_bpermute_b32 v51, v176, v64
	v_mul_f32_e32 v65, v65, v70
	v_mul_f32_e32 v65, v65, v68
	v_cndmask_b32_e64 v49, v49, -v49, s[6:7]
	v_fmac_f32_e32 v49, v50, v56
	ds_bpermute_b32 v50, v176, v65
	s_waitcnt lgkmcnt(1)
	v_mul_f32_e32 v45, v45, v51
	v_cndmask_b32_e64 v45, v45, -v45, s[6:7]
	v_fmac_f32_e32 v45, v44, v64
	v_cndmask_b32_e64 v44, v64, v45, s[4:5]
	s_waitcnt lgkmcnt(0)
	v_mul_f32_e32 v45, v47, v50
	ds_bpermute_b32 v47, v176, v59
	v_cndmask_b32_e64 v45, v45, -v45, s[6:7]
	v_fmac_f32_e32 v45, v46, v65
	ds_bpermute_b32 v46, v176, v58
	v_cndmask_b32_e64 v53, v61, v53, s[4:5]
	s_waitcnt lgkmcnt(1)
	v_mul_f32_e32 v41, v41, v47
	v_cndmask_b32_e64 v41, v41, -v41, s[6:7]
	v_fmac_f32_e32 v41, v40, v59
	s_waitcnt lgkmcnt(0)
; __device__ __forceinline__ unsigned cvt_pk_bf16(float lo, float hi) { unsigned r; asm volatile("v_cvt_pk_bf16_f32 %0, %1, %2" : "=v"(r) : "v"(lo), "v"(hi)); return r; }
; __device__ __forceinline__ float shx(float v, int m, int lane) { return __int_as_float(__builtin_amdgcn_ds_bpermute((lane ^ m) << 2, __float_as_int(v))); }
; #define DPPF(v, ctrl) __int_as_float(__builtin_amdgcn_update_dpp(0, __float_as_int(v), (ctrl), 0xf, 0xf, false))
; __device__ __forceinline__ float row16_sum(float x) { x += DPPF(x, 0xB1); x += DPPF(x, 0x4E); x += DPPF(x, 0x141); x += DPPF(x, 0x140); return x; }
; template <bool NORM, int ROT> __device__ __forceinline__ void rope_chunk(bf16_t* p, const u32x4 w, const f32x4 (&tb)[4], const float* g, float sc, int lane) {
;     ...
;         float ss = 0.f;
; #pragma unroll
;         for (int q = 0; q < 8; ++q) ss += x[q] * x[q];
;         ss = row16_sum(ss);
;         const float rstd = rsqrtf(ss * (1.f / 128.f) + EPS);
;         const f32x4 g0 = *(const f32x4*)(g + j * 8), g1 = *(const f32x4*)(g + j * 8 + 4);
; #pragma unroll
;         for (int q = 0; q < 4; ++q) { x[q] *= rstd * g0[q]; x[4 + q] *= rstd * g1[q]; }
;     }
;     constexpr int HALFL = ROT / 16;
;     const bool rot = (ROT == 128) || (j < 8); const bool first = (j & HALFL) == 0;
;     float o[8];
; #pragma unroll
;     for (int q = 0; q < 8; ++q) {
;         const float other = (ROT == 128) ? DPPF(x[q], 0x128)   : shx(x[q], HALFL, lane);
;         const float cs = tb[q >> 1][(q & 1) * 2], sn = tb[q >> 1][(q & 1) * 2 + 1];
;         const float r = first ? (x[q] * cs - other * sn) : (x[q] * cs + other * sn);
;         o[q] = (rot ? r : x[q]) * sc;
;     }
;     u32x4 ow; ow.x = cvt_pk_bf16(o[0], o[1]); ow.y = cvt_pk_bf16(o[2], o[3]); ow.z = cvt_pk_bf16(o[4], o[5]); ow.w = cvt_pk_bf16(o[6], o[7]);
;     *(u32x4*)(p + lane * 8) = ow;
	v_mul_f32_e32 v40, v43, v46
	v_cndmask_b32_e64 v40, v40, -v40, s[6:7]
	v_fmac_f32_e32 v40, v42, v58
	v_cndmask_b32_e64 v43, v58, v40, s[4:5]
	v_cndmask_b32_e64 v49, v56, v49, s[4:5]
	v_cndmask_b32_e64 v45, v65, v45, s[4:5]
	v_cndmask_b32_e64 v47, v59, v41, s[4:5]
	v_cvt_pk_bf16_f32 v40, v52, v53
	v_cvt_pk_bf16_f32 v41, v48, v49
	v_cvt_pk_bf16_f32 v42, v44, v45
	v_cvt_pk_bf16_f32 v43, v47, v43
	flat_store_dwordx4 v[164:165], v[40:43]
	flat_load_dwordx4 v[40:43], v[160:161]
	s_nop 0
	flat_load_dwordx4 v[44:47], v[160:161] offset:16
	v_and_b32_e32 v53, 0xffff0000, v36
	v_lshlrev_b32_e32 v52, 16, v36
	v_mul_f32_e32 v50, v53, v53
	v_and_b32_e32 v36, 0xffff0000, v37
	v_lshlrev_b32_e32 v37, 16, v37
	v_fmac_f32_e32 v50, v52, v52
	v_pk_mul_f32 v[48:49], v[36:37], v[36:37]
	s_nop 0
	v_add_f32_e32 v49, v49, v50
	v_add_f32_e32 v54, v48, v49
	v_and_b32_e32 v48, 0xffff0000, v38
	v_lshlrev_b32_e32 v49, 16, v38
	v_pk_mul_f32 v[50:51], v[48:49], v[48:49]
	s_nop 0
	v_add_f32_e32 v38, v51, v54
	v_add_f32_e32 v54, v50, v38
	v_and_b32_e32 v38, 0xffff0000, v39
	v_lshlrev_b32_e32 v39, 16, v39
	v_pk_mul_f32 v[50:51], v[38:39], v[38:39]
	s_nop 0
	v_add_f32_e32 v51, v51, v54
	v_add_f32_e32 v50, v50, v51
	s_nop 1
	v_add_f32_dpp v50, v50, v50 quad_perm:[1,0,3,2] row_mask:0xf bank_mask:0xf bound_ctrl:1
	s_nop 1
	v_add_f32_dpp v50, v50, v50 quad_perm:[2,3,0,1] row_mask:0xf bank_mask:0xf bound_ctrl:1
	s_nop 1
	v_add_f32_dpp v50, v50, v50 row_half_mirror row_mask:0xf bank_mask:0xf bound_ctrl:1
	s_nop 1
	v_add_f32_dpp v50, v50, v50 row_mirror row_mask:0xf bank_mask:0xf bound_ctrl:1
	v_fmamk_f32 v50, v50, 0x3c000000, v177
	v_mul_f32_e32 v51, 0x4b800000, v50
	v_cmp_gt_f32_e32 vcc, s19, v50
	s_nop 1
	v_cndmask_b32_e32 v50, v50, v51, vcc
	v_rsq_f32_e32 v50, v50
	s_nop 0
	v_mul_f32_e32 v51, 0x45800000, v50
	v_cndmask_b32_e32 v50, v50, v51, vcc
	s_waitcnt vmcnt(0) lgkmcnt(0)
	v_mul_f32_e32 v40, v40, v50
	v_mul_f32_e32 v42, v42, v50
	v_mul_f32_e32 v40, v40, v52
	v_mul_f32_e32 v37, v42, v37
	v_mul_f32_e32 v42, v46, v50
	v_mul_f32_e32 v39, v42, v39
	v_mul_f32_e32 v42, v43, v50
	ds_bpermute_b32 v43, v176, v40
	v_mul_f32_e32 v41, v41, v50
	v_mul_f32_e32 v41, v41, v53
	v_mul_f32_e32 v36, v42, v36
	v_mul_f32_e32 v42, v47, v50
	v_mul_f32_e32 v38, v42, v38
	ds_bpermute_b32 v42, v176, v41
	s_waitcnt lgkmcnt(1)
	v_mul_f32_e32 v33, v33, v43
	v_cndmask_b32_e64 v33, v33, -v33, s[6:7]
	v_fmac_f32_e32 v33, v32, v40
	v_cndmask_b32_e64 v32, v40, v33, s[4:5]
	s_waitcnt lgkmcnt(0)
	v_mul_f32_e32 v33, v35, v42
	ds_bpermute_b32 v35, v176, v37
	v_cndmask_b32_e64 v33, v33, -v33, s[6:7]
	v_fmac_f32_e32 v33, v34, v41
	ds_bpermute_b32 v34, v176, v36
	v_mul_f32_e32 v44, v44, v50
	s_waitcnt lgkmcnt(1)
	v_mul_f32_e32 v29, v29, v35
	v_cndmask_b32_e64 v29, v29, -v29, s[6:7]
	v_mul_f32_e32 v44, v44, v49
	v_fmac_f32_e32 v29, v28, v37
	v_cndmask_b32_e64 v28, v37, v29, s[4:5]
	s_waitcnt lgkmcnt(0)
	v_mul_f32_e32 v29, v31, v34
	ds_bpermute_b32 v31, v176, v44
	v_mul_f32_e32 v45, v45, v50
	v_mul_f32_e32 v45, v45, v48
	v_cndmask_b32_e64 v29, v29, -v29, s[6:7]
	v_fmac_f32_e32 v29, v30, v36
	ds_bpermute_b32 v30, v176, v45
	s_waitcnt lgkmcnt(1)
	v_mul_f32_e32 v25, v25, v31
	v_cndmask_b32_e64 v25, v25, -v25, s[6:7]
	v_fmac_f32_e32 v25, v24, v44
	v_cndmask_b32_e64 v24, v44, v25, s[4:5]
	s_waitcnt lgkmcnt(0)
	v_mul_f32_e32 v25, v27, v30
	ds_bpermute_b32 v27, v176, v39
	v_cndmask_b32_e64 v25, v25, -v25, s[6:7]
	v_fmac_f32_e32 v25, v26, v45
	ds_bpermute_b32 v26, v176, v38
	v_cndmask_b32_e64 v33, v41, v33, s[4:5]
	s_waitcnt lgkmcnt(1)
	v_mul_f32_e32 v21, v21, v27
	v_cndmask_b32_e64 v21, v21, -v21, s[6:7]
	v_fmac_f32_e32 v21, v20, v39
	s_waitcnt lgkmcnt(0)
; __device__ __forceinline__ unsigned cvt_pk_bf16(float lo, float hi) { unsigned r; asm volatile("v_cvt_pk_bf16_f32 %0, %1, %2" : "=v"(r) : "v"(lo), "v"(hi)); return r; }
; __device__ __forceinline__ float shx(float v, int m, int lane) { return __int_as_float(__builtin_amdgcn_ds_bpermute((lane ^ m) << 2, __float_as_int(v))); }
; #define DPPF(v, ctrl) __int_as_float(__builtin_amdgcn_update_dpp(0, __float_as_int(v), (ctrl), 0xf, 0xf, false))
; __device__ __forceinline__ float row16_sum(float x) { x += DPPF(x, 0xB1); x += DPPF(x, 0x4E); x += DPPF(x, 0x141); x += DPPF(x, 0x140); return x; }
; template <bool NORM, int ROT> __device__ __forceinline__ void rope_chunk(bf16_t* p, const u32x4 w, const f32x4 (&tb)[4], const float* g, float sc, int lane) {
;     ...
;         float ss = 0.f;
; #pragma unroll
;         for (int q = 0; q < 8; ++q) ss += x[q] * x[q];
;         ss = row16_sum(ss);
;         const float rstd = rsqrtf(ss * (1.f / 128.f) + EPS);
;         const f32x4 g0 = *(const f32x4*)(g + j * 8), g1 = *(const f32x4*)(g + j * 8 + 4);
; #pragma unroll
;         for (int q = 0; q < 4; ++q) { x[q] *= rstd * g0[q]; x[4 + q] *= rstd * g1[q]; }
;     }
;     constexpr int HALFL = ROT / 16;
;     const bool rot = (ROT == 128) || (j < 8); const bool first = (j & HALFL) == 0;
;     float o[8];
; #pragma unroll
;     for (int q = 0; q < 8; ++q) {
;         const float other = (ROT == 128) ? DPPF(x[q], 0x128)   : shx(x[q], HALFL, lane);
;         const float cs = tb[q >> 1][(q & 1) * 2], sn = tb[q >> 1][(q & 1) * 2 + 1];
;         const float r = first ? (x[q] * cs - other * sn) : (x[q] * cs + other * sn);
;         o[q] = (rot ? r : x[q]) * sc;
;     }
;     u32x4 ow; ow.x = cvt_pk_bf16(o[0], o[1]); ow.y = cvt_pk_bf16(o[2], o[3]); ow.z = cvt_pk_bf16(o[4], o[5]); ow.w = cvt_pk_bf16(o[6], o[7]);
;     *(u32x4*)(p + lane * 8) = ow;
; template <bool NORM, int ROT, bool PERTOK> __device__ __forceinline__ void rope_pass(bf16_t* base, int nchunks, const float* g, const float* tab, float sc, int gw, int NGW, int lane) {
;     ...
;     for (int it0 = gw * NB; it0 < nchunks; it0 += NGW * NB) {
	v_mul_f32_e32 v20, v23, v26
	v_cndmask_b32_e64 v20, v20, -v20, s[6:7]
	v_fmac_f32_e32 v20, v22, v38
	v_cndmask_b32_e64 v23, v38, v20, s[4:5]
	v_cndmask_b32_e64 v29, v36, v29, s[4:5]
	v_cndmask_b32_e64 v25, v45, v25, s[4:5]
	v_cndmask_b32_e64 v27, v39, v21, s[4:5]
	v_cvt_pk_bf16_f32 v20, v32, v33
	v_cvt_pk_bf16_f32 v21, v28, v29
	v_cvt_pk_bf16_f32 v22, v24, v25
	v_cvt_pk_bf16_f32 v23, v27, v23
	flat_store_dwordx4 v[162:163], v[20:23]
	flat_load_dwordx4 v[20:23], v[160:161]
	s_nop 0
	flat_load_dwordx4 v[24:27], v[160:161] offset:16
	v_and_b32_e32 v33, 0xffff0000, v16
	v_lshlrev_b32_e32 v32, 16, v16
	v_mul_f32_e32 v30, v33, v33
	v_and_b32_e32 v16, 0xffff0000, v17
	v_lshlrev_b32_e32 v17, 16, v17
	v_fmac_f32_e32 v30, v32, v32
	v_pk_mul_f32 v[28:29], v[16:17], v[16:17]
	s_nop 0
	v_add_f32_e32 v29, v29, v30
	v_add_f32_e32 v34, v28, v29
	v_and_b32_e32 v28, 0xffff0000, v18
	v_lshlrev_b32_e32 v29, 16, v18
	v_pk_mul_f32 v[30:31], v[28:29], v[28:29]
	s_nop 0
	v_add_f32_e32 v18, v31, v34
	v_add_f32_e32 v34, v30, v18
	v_and_b32_e32 v18, 0xffff0000, v19
	v_lshlrev_b32_e32 v19, 16, v19
	v_pk_mul_f32 v[30:31], v[18:19], v[18:19]
	s_nop 0
	v_add_f32_e32 v31, v31, v34
	v_add_f32_e32 v30, v30, v31
	s_nop 1
	v_add_f32_dpp v30, v30, v30 quad_perm:[1,0,3,2] row_mask:0xf bank_mask:0xf bound_ctrl:1
	s_nop 1
	v_add_f32_dpp v30, v30, v30 quad_perm:[2,3,0,1] row_mask:0xf bank_mask:0xf bound_ctrl:1
	s_nop 1
	v_add_f32_dpp v30, v30, v30 row_half_mirror row_mask:0xf bank_mask:0xf bound_ctrl:1
	s_nop 1
	v_add_f32_dpp v30, v30, v30 row_mirror row_mask:0xf bank_mask:0xf bound_ctrl:1
	v_fmamk_f32 v30, v30, 0x3c000000, v177
	v_mul_f32_e32 v31, 0x4b800000, v30
	v_cmp_gt_f32_e32 vcc, s19, v30
	s_nop 1
	v_cndmask_b32_e32 v30, v30, v31, vcc
	v_rsq_f32_e32 v30, v30
	s_nop 0
	v_mul_f32_e32 v31, 0x45800000, v30
	v_cndmask_b32_e32 v30, v30, v31, vcc
	s_waitcnt vmcnt(0) lgkmcnt(0)
	v_mul_f32_e32 v20, v20, v30
	v_mul_f32_e32 v22, v22, v30
	v_mul_f32_e32 v20, v20, v32
	v_mul_f32_e32 v17, v22, v17
	v_mul_f32_e32 v22, v26, v30
	v_mul_f32_e32 v19, v22, v19
	v_mul_f32_e32 v22, v23, v30
	ds_bpermute_b32 v23, v176, v20
	v_mul_f32_e32 v21, v21, v30
	v_mul_f32_e32 v21, v21, v33
	v_mul_f32_e32 v16, v22, v16
	v_mul_f32_e32 v22, v27, v30
	v_mul_f32_e32 v18, v22, v18
	ds_bpermute_b32 v22, v176, v21
	s_waitcnt lgkmcnt(1)
	v_mul_f32_e32 v13, v13, v23
	v_cndmask_b32_e64 v13, v13, -v13, s[6:7]
	v_fmac_f32_e32 v13, v12, v20
	v_cndmask_b32_e64 v12, v20, v13, s[4:5]
	s_waitcnt lgkmcnt(0)
	v_mul_f32_e32 v13, v15, v22
	ds_bpermute_b32 v15, v176, v17
	v_cndmask_b32_e64 v13, v13, -v13, s[6:7]
	v_fmac_f32_e32 v13, v14, v21
	ds_bpermute_b32 v14, v176, v16
	v_mul_f32_e32 v24, v24, v30
	s_waitcnt lgkmcnt(1)
	v_mul_f32_e32 v9, v9, v15
	v_cndmask_b32_e64 v9, v9, -v9, s[6:7]
	v_mul_f32_e32 v24, v24, v29
	v_fmac_f32_e32 v9, v8, v17
	v_cndmask_b32_e64 v8, v17, v9, s[4:5]
	s_waitcnt lgkmcnt(0)
	v_mul_f32_e32 v9, v11, v14
	ds_bpermute_b32 v11, v176, v24
	v_mul_f32_e32 v25, v25, v30
	v_mul_f32_e32 v25, v25, v28
	v_cndmask_b32_e64 v9, v9, -v9, s[6:7]
	v_fmac_f32_e32 v9, v10, v16
	ds_bpermute_b32 v10, v176, v25
	s_waitcnt lgkmcnt(1)
	v_mul_f32_e32 v5, v5, v11
	v_cndmask_b32_e64 v5, v5, -v5, s[6:7]
	v_fmac_f32_e32 v5, v4, v24
	v_cndmask_b32_e64 v4, v24, v5, s[4:5]
	s_waitcnt lgkmcnt(0)
	v_mul_f32_e32 v5, v7, v10
	ds_bpermute_b32 v7, v176, v19
	v_cndmask_b32_e64 v5, v5, -v5, s[6:7]
	v_fmac_f32_e32 v5, v6, v25
	ds_bpermute_b32 v6, v176, v18
	v_cndmask_b32_e64 v13, v21, v13, s[4:5]
	s_waitcnt lgkmcnt(1)
	v_mul_f32_e32 v1, v1, v7
	v_cndmask_b32_e64 v1, v1, -v1, s[6:7]
	v_fmac_f32_e32 v1, v0, v19
	s_waitcnt lgkmcnt(0)
	v_mul_f32_e32 v0, v3, v6
	v_cndmask_b32_e64 v0, v0, -v0, s[6:7]
	v_fmac_f32_e32 v0, v2, v18
	v_cndmask_b32_e64 v3, v18, v0, s[4:5]
	v_cndmask_b32_e64 v9, v16, v9, s[4:5]
	v_cndmask_b32_e64 v5, v25, v5, s[4:5]
	v_cndmask_b32_e64 v7, v19, v1, s[4:5]
	v_cvt_pk_bf16_f32 v0, v12, v13
	v_cvt_pk_bf16_f32 v1, v8, v9
	v_cvt_pk_bf16_f32 v2, v4, v5
	v_cvt_pk_bf16_f32 v3, v7, v3
	flat_store_dwordx4 v[156:157], v[0:3]
	v_lshl_add_u64 v[156:157], v[156:157], 0, s[10:11]
	s_cbranch_scc1 .Lri_1080
.Lri_1081:
	v_readlane_b32 s91, v255, 3
	s_cmp_lt_u32 s91, 4
	s_cbranch_scc1 .LBB0_2874
	s_branch .Lsel_a_go
